# M3 tail (CBt + 4-head loop) hand-rewritten with transposed tiles, 8B loads/stores
# speedup vs baseline: 1.0288x; 1.0288x over previous
; DI f32x4 mfma16(bf16x8 a, bf16x8 b, f32x4 c) { return __builtin_amdgcn_mfma_f32_16x16x32_bf16(a, b, c, 0, 0, 0); }
; __global__ void __launch_bounds__(512, 2) fwd_megakernel(Args args) {
;     ...
;                 __syncthreads();
;                 {
;                     const int lrow = 16 * wave + r16;
;                     bf16x8 ca[4];
; #pragma unroll
;                     for (int ks = 0; ks < 4; ++ks) ca[ks] = lds_frag(Cs, lrow, 136, ks * 32 + q4 * 8);
;                     f32x4 cbr[8];
; #pragma unroll
;                     for (int st = 0; st < 8; ++st) {
;                         cbr[st] = (f32x4){0.f, 0.f, 0.f, 0.f};
;                         if (st <= wave) {
; #pragma unroll
;                             for (int ks = 0; ks < 4; ++ks) cbr[st] = mfma16(ca[ks], lds_frag(Bs, 16 * st + r16, 136, ks * 32 + q4 * 8), cbr[st]);
;                         }
;                     }
;                     __syncthreads();
; #pragma unroll 1
;                     for (int hh = 0; hh < 4; ++hh) {
;                         const int h = g2 * 4 + hh; const int unit8 = ((b * NCH + c) * 8) + h;
;                         bf16x8 pvf[4][4];
;                         {
;                             const bf16* pv = PV + (size_t)unit8 * 8192;
; #pragma unroll
;                             for (int ks = 0; ks < 4; ++ks)
; #pragma unroll
;                                 for (int pt = 0; pt < 4; ++pt) pvf[ks][pt] = *(const bf16x8*)(pv + (16 * pt + r16) * 128 + ks * 32 + q4 * 8);
;                         }
;                         bf16 zr[4][4];
; #pragma unroll
;                         for (int j = 0; j < 4; ++j)
; #pragma unroll
;                             for (int pt = 0; pt < 4; ++pt) zr[j][pt] = proj[(grow0 + 16 * wave + q4 * 4 + j) * NPROJ + PC_Z + h * 64 + 16 * pt + r16];
.LBB0_973:
	s_waitcnt vmcnt(0) lgkmcnt(0)
	s_mov_b32 s78, s91
	s_mov_b64 s[90:91], s[92:93]
	s_mov_b64 s[92:93], s[84:85]
	s_mov_b64 s[84:85], s[94:95]
	s_mov_b64 s[96:97], s[28:29]
	s_mov_b32 s79, s59
	s_mov_b32 s33, s86
	s_lshr_b32 s2, s86, 4
	v_and_b32_e32 v176, 15, v232
	v_bfe_u32 v177, v232, 4, 2
	v_mul_u32_u24_e32 v178, 0x110, v176
	v_lshl_add_u32 v178, v177, 4, v178
	s_mul_i32 s4, s2, 0x1100
	v_add_u32_e32 v179, s4, v178
	v_readlane_b32 s24, v251, 31
	v_readlane_b32 s25, v251, 32
	v_readlane_b32 s5, v253, 58
	s_and_b32 s6, s83, 1
	s_lshl_b32 s7, s6, 2
	s_add_i32 s5, s5, s7
	s_lshl_b32 s5, s5, 2
	s_add_u32 s24, s24, s5
	s_addc_u32 s25, s25, 0
	s_load_dwordx4 s[36:39], s[24:25], 0x0
	s_lshl_b32 s7, s83, 16
	s_add_u32 s8, s80, 0x12000000
	s_addc_u32 s9, s81, 0
	s_add_u32 s8, s8, s7
	s_addc_u32 s9, s9, 0
	s_lshr_b32 s7, s83, 1
	s_mul_i32 s12, s7, 0xb0000
	s_lshl_b32 s13, s6, 9
	s_add_u32 s12, s12, s13
	s_add_u32 s10, s80, 0x15000000
	s_addc_u32 s11, s81, 0
	s_add_u32 s10, s10, s12
	s_addc_u32 s11, s11, 0
	s_lshl_b32 s12, s7, 18
	s_add_u32 s12, s12, s13
	s_add_u32 s22, s80, 0xa000000
	s_addc_u32 s23, s81, 0
	s_add_u32 s12, s22, s12
	s_addc_u32 s13, s23, 0
	s_lshl_b32 s22, s6, 19
	s_lshl_b32 s23, s7, 11
	s_add_u32 s22, s22, s23
	s_add_u32 s26, s80, 0x300000
	s_addc_u32 s27, s81, 0
	s_add_u32 s22, s26, s22
	s_addc_u32 s23, s27, 0
	v_lshlrev_b32_e32 v180, 8, v176
	v_lshl_add_u32 v180, v177, 4, v180
	v_add_u32_e32 v181, 0x1000, v180
	v_add_u32_e32 v182, 0x2000, v180
	v_add_u32_e32 v183, 0x3000, v180
	v_lshl_add_u32 v213, s2, 4, v176
	v_mul_u32_u24_e32 v184, 0x1600, v213
	v_lshl_add_u32 v184, v177, 3, v184
	v_lshlrev_b32_e32 v185, 11, v213
	v_lshl_add_u32 v185, v177, 3, v185
	v_lshlrev_b32_e32 v186, 4, v213
	v_lshlrev_b32_e32 v187, 2, v213
	v_add_u32_e32 v187, 0x22000, v187
	v_lshlrev_b32_e32 v188, 4, v177
	v_add_u32_e32 v188, 0x22000, v188
	v_mul_u32_u24_e32 v189, 0x110, v213
	v_lshl_add_u32 v189, v177, 3, v189
	v_add_u32_e32 v189, 0x8800, v189
	v_add_u32_e32 v190, 0x11000, v178
	v_mul_u32_u24_e32 v191, 0x440, v177
	v_lshl_add_u32 v191, v213, 1, v191
	v_add_u32_e32 v191, 0x11000, v191
	v_mov_b32_e32 v214, 0
	v_mov_b32_e32 v215, 0
	v_and_b32_e32 v213, 63, v232
	v_xor_b32_e32 v211, 16, v213
	v_lshlrev_b32_e32 v211, 2, v211
	v_xor_b32_e32 v212, 32, v213
	v_lshlrev_b32_e32 v212, 2, v212
	v_lshlrev_b32_e32 v213, 2, v177
	v_add_u32_e32 v160, 0, v213
	v_cmp_le_u32_e64 s[44:45], v160, v176
	v_add_u32_e32 v160, 1, v213
	v_cmp_le_u32_e64 s[46:47], v160, v176
	v_add_u32_e32 v160, 2, v213
	v_cmp_le_u32_e64 s[48:49], v160, v176
	v_add_u32_e32 v160, 3, v213
	v_cmp_le_u32_e64 s[50:51], v160, v176
	v_cmp_eq_u32_e64 s[42:43], 0, v177
	s_waitcnt vmcnt(0) lgkmcnt(0)
	s_barrier
	global_load_dwordx4 v[48:51], v180, s[8:9] offset:0
	global_load_dwordx4 v[52:55], v181, s[8:9] offset:0
	global_load_dwordx4 v[56:59], v182, s[8:9] offset:0
	global_load_dwordx4 v[60:63], v183, s[8:9] offset:0
	global_load_dwordx4 v[64:67], v180, s[8:9] offset:64
	global_load_dwordx4 v[68:71], v181, s[8:9] offset:64
	global_load_dwordx4 v[72:75], v182, s[8:9] offset:64
	global_load_dwordx4 v[76:79], v183, s[8:9] offset:64
	global_load_dwordx4 v[80:83], v180, s[8:9] offset:128
	global_load_dwordx4 v[84:87], v181, s[8:9] offset:128
	global_load_dwordx4 v[88:91], v182, s[8:9] offset:128
	global_load_dwordx4 v[92:95], v183, s[8:9] offset:128
	global_load_dwordx4 v[96:99], v180, s[8:9] offset:192
	global_load_dwordx4 v[100:103], v181, s[8:9] offset:192
	global_load_dwordx4 v[104:107], v182, s[8:9] offset:192
	global_load_dwordx4 v[108:111], v183, s[8:9] offset:192
	global_load_dwordx2 v[128:129], v184, s[10:11] offset:0
	global_load_dwordx2 v[130:131], v184, s[10:11] offset:32
	global_load_dwordx2 v[132:133], v184, s[10:11] offset:64
	global_load_dwordx2 v[134:135], v184, s[10:11] offset:96
	ds_read_b128 v[32:35], v179 offset:0
	ds_read_b128 v[36:39], v179 offset:64
	ds_read_b128 v[40:43], v179 offset:128
	ds_read_b128 v[44:47], v179 offset:192
	ds_read_b128 v[160:163], v178 offset:34816
	ds_read_b128 v[164:167], v178 offset:34880
	ds_read_b128 v[168:171], v178 offset:34944
	ds_read_b128 v[172:175], v178 offset:35008
	s_cmp_lt_u32 s2, 1
	s_cbranch_scc1 .Lm3_cb_last0
	ds_read_b128 v[136:139], v178 offset:39168
	ds_read_b128 v[140:143], v178 offset:39232
	ds_read_b128 v[144:147], v178 offset:39296
	ds_read_b128 v[148:151], v178 offset:39360
	s_waitcnt lgkmcnt(4)
	v_mfma_f32_16x16x32_bf16 v[0:3], v[160:163], v[32:35], 0
	v_mfma_f32_16x16x32_bf16 v[0:3], v[164:167], v[36:39], v[0:3]
	v_mfma_f32_16x16x32_bf16 v[0:3], v[168:171], v[40:43], v[0:3]
	v_mfma_f32_16x16x32_bf16 v[0:3], v[172:175], v[44:47], v[0:3]
	s_branch .Lm3_cb_next0
.Lm3_cb_last0:
	s_waitcnt lgkmcnt(0)
	v_mfma_f32_16x16x32_bf16 v[0:3], v[160:163], v[32:35], 0
	v_mfma_f32_16x16x32_bf16 v[0:3], v[164:167], v[36:39], v[0:3]
	v_mfma_f32_16x16x32_bf16 v[0:3], v[168:171], v[40:43], v[0:3]
	v_mfma_f32_16x16x32_bf16 v[0:3], v[172:175], v[44:47], v[0:3]
	s_branch .Lm3_cb_done
.Lm3_cb_next0:
	s_cmp_lt_u32 s2, 2
	s_cbranch_scc1 .Lm3_cb_last1
	ds_read_b128 v[160:163], v178 offset:43520
	ds_read_b128 v[164:167], v178 offset:43584
	ds_read_b128 v[168:171], v178 offset:43648
	ds_read_b128 v[172:175], v178 offset:43712
	s_waitcnt lgkmcnt(4)
	v_mfma_f32_16x16x32_bf16 v[4:7], v[136:139], v[32:35], 0
	v_mfma_f32_16x16x32_bf16 v[4:7], v[140:143], v[36:39], v[4:7]
	v_mfma_f32_16x16x32_bf16 v[4:7], v[144:147], v[40:43], v[4:7]
	v_mfma_f32_16x16x32_bf16 v[4:7], v[148:151], v[44:47], v[4:7]
	s_branch .Lm3_cb_next1
; DI f32x4 mfma16(bf16x8 a, bf16x8 b, f32x4 c) { return __builtin_amdgcn_mfma_f32_16x16x32_bf16(a, b, c, 0, 0, 0); }
; __global__ void __launch_bounds__(512, 2) fwd_megakernel(Args args) {
;     ...
;                     f32x4 cbr[8];
; #pragma unroll
;                     for (int st = 0; st < 8; ++st) {
;                         cbr[st] = (f32x4){0.f, 0.f, 0.f, 0.f};
;                         if (st <= wave) {
; #pragma unroll
;                             for (int ks = 0; ks < 4; ++ks) cbr[st] = mfma16(ca[ks], lds_frag(Bs, 16 * st + r16, 136, ks * 32 + q4 * 8), cbr[st]);
;                         }
;                     }
.Lm3_cb_last1:
	s_waitcnt lgkmcnt(0)
	v_mfma_f32_16x16x32_bf16 v[4:7], v[136:139], v[32:35], 0
	v_mfma_f32_16x16x32_bf16 v[4:7], v[140:143], v[36:39], v[4:7]
	v_mfma_f32_16x16x32_bf16 v[4:7], v[144:147], v[40:43], v[4:7]
	v_mfma_f32_16x16x32_bf16 v[4:7], v[148:151], v[44:47], v[4:7]
	s_branch .Lm3_cb_done
.Lm3_cb_next1:
	s_cmp_lt_u32 s2, 3
	s_cbranch_scc1 .Lm3_cb_last2
	ds_read_b128 v[136:139], v178 offset:47872
	ds_read_b128 v[140:143], v178 offset:47936
	ds_read_b128 v[144:147], v178 offset:48000
	ds_read_b128 v[148:151], v178 offset:48064
	s_waitcnt lgkmcnt(4)
	v_mfma_f32_16x16x32_bf16 v[8:11], v[160:163], v[32:35], 0
	v_mfma_f32_16x16x32_bf16 v[8:11], v[164:167], v[36:39], v[8:11]
	v_mfma_f32_16x16x32_bf16 v[8:11], v[168:171], v[40:43], v[8:11]
	v_mfma_f32_16x16x32_bf16 v[8:11], v[172:175], v[44:47], v[8:11]
	s_branch .Lm3_cb_next2
.Lm3_cb_last2:
	s_waitcnt lgkmcnt(0)
	v_mfma_f32_16x16x32_bf16 v[8:11], v[160:163], v[32:35], 0
	v_mfma_f32_16x16x32_bf16 v[8:11], v[164:167], v[36:39], v[8:11]
	v_mfma_f32_16x16x32_bf16 v[8:11], v[168:171], v[40:43], v[8:11]
	v_mfma_f32_16x16x32_bf16 v[8:11], v[172:175], v[44:47], v[8:11]
	s_branch .Lm3_cb_done
.Lm3_cb_next2:
	s_cmp_lt_u32 s2, 4
	s_cbranch_scc1 .Lm3_cb_last3
	ds_read_b128 v[160:163], v178 offset:52224
	ds_read_b128 v[164:167], v178 offset:52288
	ds_read_b128 v[168:171], v178 offset:52352
	ds_read_b128 v[172:175], v178 offset:52416
	s_waitcnt lgkmcnt(4)
	v_mfma_f32_16x16x32_bf16 v[12:15], v[136:139], v[32:35], 0
	v_mfma_f32_16x16x32_bf16 v[12:15], v[140:143], v[36:39], v[12:15]
	v_mfma_f32_16x16x32_bf16 v[12:15], v[144:147], v[40:43], v[12:15]
	v_mfma_f32_16x16x32_bf16 v[12:15], v[148:151], v[44:47], v[12:15]
	s_branch .Lm3_cb_next3
.Lm3_cb_last3:
	s_waitcnt lgkmcnt(0)
	v_mfma_f32_16x16x32_bf16 v[12:15], v[136:139], v[32:35], 0
	v_mfma_f32_16x16x32_bf16 v[12:15], v[140:143], v[36:39], v[12:15]
	v_mfma_f32_16x16x32_bf16 v[12:15], v[144:147], v[40:43], v[12:15]
	v_mfma_f32_16x16x32_bf16 v[12:15], v[148:151], v[44:47], v[12:15]
	s_branch .Lm3_cb_done
.Lm3_cb_next3:
	s_cmp_lt_u32 s2, 5
	s_cbranch_scc1 .Lm3_cb_last4
	ds_read_b128 v[136:139], v178 offset:56576
	ds_read_b128 v[140:143], v178 offset:56640
	ds_read_b128 v[144:147], v178 offset:56704
	ds_read_b128 v[148:151], v178 offset:56768
	s_waitcnt lgkmcnt(4)
	v_mfma_f32_16x16x32_bf16 v[16:19], v[160:163], v[32:35], 0
	v_mfma_f32_16x16x32_bf16 v[16:19], v[164:167], v[36:39], v[16:19]
	v_mfma_f32_16x16x32_bf16 v[16:19], v[168:171], v[40:43], v[16:19]
	v_mfma_f32_16x16x32_bf16 v[16:19], v[172:175], v[44:47], v[16:19]
	s_branch .Lm3_cb_next4
.Lm3_cb_last4:
	s_waitcnt lgkmcnt(0)
	v_mfma_f32_16x16x32_bf16 v[16:19], v[160:163], v[32:35], 0
	v_mfma_f32_16x16x32_bf16 v[16:19], v[164:167], v[36:39], v[16:19]
	v_mfma_f32_16x16x32_bf16 v[16:19], v[168:171], v[40:43], v[16:19]
	v_mfma_f32_16x16x32_bf16 v[16:19], v[172:175], v[44:47], v[16:19]
	s_branch .Lm3_cb_done
.Lm3_cb_next4:
	s_cmp_lt_u32 s2, 6
	s_cbranch_scc1 .Lm3_cb_last5
	ds_read_b128 v[160:163], v178 offset:60928
	ds_read_b128 v[164:167], v178 offset:60992
	ds_read_b128 v[168:171], v178 offset:61056
	ds_read_b128 v[172:175], v178 offset:61120
	s_waitcnt lgkmcnt(4)
	v_mfma_f32_16x16x32_bf16 v[20:23], v[136:139], v[32:35], 0
	v_mfma_f32_16x16x32_bf16 v[20:23], v[140:143], v[36:39], v[20:23]
	v_mfma_f32_16x16x32_bf16 v[20:23], v[144:147], v[40:43], v[20:23]
	v_mfma_f32_16x16x32_bf16 v[20:23], v[148:151], v[44:47], v[20:23]
	s_branch .Lm3_cb_next5
.Lm3_cb_last5:
	s_waitcnt lgkmcnt(0)
	v_mfma_f32_16x16x32_bf16 v[20:23], v[136:139], v[32:35], 0
	v_mfma_f32_16x16x32_bf16 v[20:23], v[140:143], v[36:39], v[20:23]
	v_mfma_f32_16x16x32_bf16 v[20:23], v[144:147], v[40:43], v[20:23]
	v_mfma_f32_16x16x32_bf16 v[20:23], v[148:151], v[44:47], v[20:23]
	s_branch .Lm3_cb_done
.Lm3_cb_next5:
	s_cmp_lt_u32 s2, 7
	s_cbranch_scc1 .Lm3_cb_last6
	ds_read_b128 v[136:139], v178 offset:65280
	ds_read_b128 v[140:143], v178 offset:65344
	ds_read_b128 v[144:147], v178 offset:65408
	ds_read_b128 v[148:151], v178 offset:65472
	s_waitcnt lgkmcnt(4)
	v_mfma_f32_16x16x32_bf16 v[24:27], v[160:163], v[32:35], 0
	v_mfma_f32_16x16x32_bf16 v[24:27], v[164:167], v[36:39], v[24:27]
	v_mfma_f32_16x16x32_bf16 v[24:27], v[168:171], v[40:43], v[24:27]
	v_mfma_f32_16x16x32_bf16 v[24:27], v[172:175], v[44:47], v[24:27]
	s_branch .Lm3_cb_next6
.Lm3_cb_last6:
	s_waitcnt lgkmcnt(0)
	v_mfma_f32_16x16x32_bf16 v[24:27], v[160:163], v[32:35], 0
	v_mfma_f32_16x16x32_bf16 v[24:27], v[164:167], v[36:39], v[24:27]
	v_mfma_f32_16x16x32_bf16 v[24:27], v[168:171], v[40:43], v[24:27]
	v_mfma_f32_16x16x32_bf16 v[24:27], v[172:175], v[44:47], v[24:27]
	s_branch .Lm3_cb_done
.Lm3_cb_next6:
	s_waitcnt lgkmcnt(0)
	v_mfma_f32_16x16x32_bf16 v[28:31], v[136:139], v[32:35], 0
	v_mfma_f32_16x16x32_bf16 v[28:31], v[140:143], v[36:39], v[28:31]
	v_mfma_f32_16x16x32_bf16 v[28:31], v[144:147], v[40:43], v[28:31]
	v_mfma_f32_16x16x32_bf16 v[28:31], v[148:151], v[44:47], v[28:31]
; #define LAS __attribute__((address_space(3)))
; DI unsigned short f2bf(float f) { return (unsigned short)(pk2(f, 0.f) & 0xffffu); }
; __global__ void __launch_bounds__(512, 2) fwd_megakernel(Args args) {
;     ...
;                     __syncthreads();
; #pragma unroll 1
;                     for (int hh = 0; hh < 4; ++hh) {
;                         const int h = g2 * 4 + hh; const int unit8 = ((b * NCH + c) * 8) + h;
;                         bf16x8 pvf[4][4];
;                         {
;                             const bf16* pv = PV + (size_t)unit8 * 8192;
; #pragma unroll
;                             for (int ks = 0; ks < 4; ++ks)
; #pragma unroll
;                                 for (int pt = 0; pt < 4; ++pt) pvf[ks][pt] = *(const bf16x8*)(pv + (16 * pt + r16) * 128 + ks * 32 + q4 * 8);
;                         }
;                         bf16 zr[4][4];
; #pragma unroll
;                         for (int j = 0; j < 4; ++j)
; #pragma unroll
;                             for (int pt = 0; pt < 4; ++pt) zr[j][pt] = proj[(grow0 + 16 * wave + q4 * 4 + j) * NPROJ + PC_Z + h * 64 + 16 * pt + r16];
;                         const LAS float* hdt = s_dt + hh * 128; const LAS float* hacs = s_acs + hh * 128;
;                         float acl[4];
; #pragma unroll
;                         for (int j = 0; j < 4; ++j) acl[j] = hacs[16 * wave + q4 * 4 + j];
; #pragma unroll
;                         for (int st = 0; st < 8; ++st) {
;                             if (st <= (wave | 1)) {
;                                 const int sI = 16 * st + r16; const float acss = hacs[sI], dts = hdt[sI];
; #pragma unroll
;                                 for (int j = 0; j < 4; ++j) { const int l = 16 * wave + q4 * 4 + j; const float mv = (sI <= l) ? cbr[st][j] * __expf(fminf(acl[j] - acss, 0.f)) * dts : 0.f; Ms[l * 136 + sI] = f2bf(mv); }
;                             }
.Lm3_cb_done:
	s_waitcnt lgkmcnt(0)
	s_barrier
	ds_read_b32 v206, v187 offset:2048
	ds_read_b128 v[152:155], v188 offset:2048
	ds_read_b128 v[156:159], v188 offset:0
	s_cmp_eq_u32 s2, 0
	s_cselect_b64 s[52:53], s[44:45], -1
	s_cselect_b64 s[54:55], s[46:47], -1
	s_cselect_b64 s[56:57], s[48:49], -1
	s_cselect_b64 s[58:59], s[50:51], -1
	s_waitcnt lgkmcnt(0)
	v_sub_f32_e32 v160, v206, v152
	v_sub_f32_e32 v161, v206, v153
	v_sub_f32_e32 v162, v206, v154
	v_sub_f32_e32 v163, v206, v155
	v_min_f32_e32 v160, 0, v160
	v_min_f32_e32 v161, 0, v161
	v_min_f32_e32 v162, 0, v162
	v_min_f32_e32 v163, 0, v163
	v_mul_f32_e32 v160, 0x3fb8aa3b, v160
	v_mul_f32_e32 v161, 0x3fb8aa3b, v161
	v_mul_f32_e32 v162, 0x3fb8aa3b, v162
	v_mul_f32_e32 v163, 0x3fb8aa3b, v163
	v_exp_f32_e32 v160, v160
	v_exp_f32_e32 v161, v161
	v_exp_f32_e32 v162, v162
	v_exp_f32_e32 v163, v163
	s_nop 0
	v_mul_f32_e32 v160, v0, v160
	v_mul_f32_e32 v161, v1, v161
	v_mul_f32_e32 v162, v2, v162
	v_mul_f32_e32 v163, v3, v163
	v_mul_f32_e32 v160, v160, v156
	v_mul_f32_e32 v161, v161, v157
	v_mul_f32_e32 v162, v162, v158
	v_mul_f32_e32 v163, v163, v159
	v_cndmask_b32_e64 v160, 0, v160, s[52:53]
	v_cndmask_b32_e64 v161, 0, v161, s[54:55]
	v_cndmask_b32_e64 v162, 0, v162, s[56:57]
	v_cndmask_b32_e64 v163, 0, v163, s[58:59]
	v_cvt_pk_bf16_f32 v164, v160, v161
	v_cvt_pk_bf16_f32 v165, v162, v163
	ds_write_b64 v189, v[164:165] offset:0
	s_cmp_lt_u32 s2, 1
	s_cbranch_scc1 .Lm3_h0_skip1
	ds_read_b128 v[152:155], v188 offset:2112
	ds_read_b128 v[156:159], v188 offset:64
	s_cmp_eq_u32 s2, 1
	s_cselect_b64 s[52:53], s[44:45], -1
	s_cselect_b64 s[54:55], s[46:47], -1
	s_cselect_b64 s[56:57], s[48:49], -1
	s_cselect_b64 s[58:59], s[50:51], -1
	s_waitcnt lgkmcnt(0)
	v_sub_f32_e32 v160, v206, v152
	v_sub_f32_e32 v161, v206, v153
	v_sub_f32_e32 v162, v206, v154
	v_sub_f32_e32 v163, v206, v155
	v_min_f32_e32 v160, 0, v160
	v_min_f32_e32 v161, 0, v161
	v_min_f32_e32 v162, 0, v162
	v_min_f32_e32 v163, 0, v163
	v_mul_f32_e32 v160, 0x3fb8aa3b, v160
	v_mul_f32_e32 v161, 0x3fb8aa3b, v161
	v_mul_f32_e32 v162, 0x3fb8aa3b, v162
	v_mul_f32_e32 v163, 0x3fb8aa3b, v163
	v_exp_f32_e32 v160, v160
	v_exp_f32_e32 v161, v161
	v_exp_f32_e32 v162, v162
	v_exp_f32_e32 v163, v163
	s_nop 0
	v_mul_f32_e32 v160, v4, v160
	v_mul_f32_e32 v161, v5, v161
	v_mul_f32_e32 v162, v6, v162
	v_mul_f32_e32 v163, v7, v163
	v_mul_f32_e32 v160, v160, v156
	v_mul_f32_e32 v161, v161, v157
	v_mul_f32_e32 v162, v162, v158
	v_mul_f32_e32 v163, v163, v159
	v_cndmask_b32_e64 v160, 0, v160, s[52:53]
	v_cndmask_b32_e64 v161, 0, v161, s[54:55]
	v_cndmask_b32_e64 v162, 0, v162, s[56:57]
	v_cndmask_b32_e64 v163, 0, v163, s[58:59]
	v_cvt_pk_bf16_f32 v164, v160, v161
	v_cvt_pk_bf16_f32 v165, v162, v163
	ds_write_b64 v189, v[164:165] offset:32
	s_cmp_lt_u32 s2, 2
	s_cbranch_scc1 .Lm3_h0_skip2
	ds_read_b128 v[152:155], v188 offset:2176
	ds_read_b128 v[156:159], v188 offset:128
	s_cmp_eq_u32 s2, 2
	s_cselect_b64 s[52:53], s[44:45], -1
	s_cselect_b64 s[54:55], s[46:47], -1
	s_cselect_b64 s[56:57], s[48:49], -1
	s_cselect_b64 s[58:59], s[50:51], -1
	s_waitcnt lgkmcnt(0)
	v_sub_f32_e32 v160, v206, v152
	v_sub_f32_e32 v161, v206, v153
	v_sub_f32_e32 v162, v206, v154
	v_sub_f32_e32 v163, v206, v155
	v_min_f32_e32 v160, 0, v160
	v_min_f32_e32 v161, 0, v161
	v_min_f32_e32 v162, 0, v162
	v_min_f32_e32 v163, 0, v163
	v_mul_f32_e32 v160, 0x3fb8aa3b, v160
	v_mul_f32_e32 v161, 0x3fb8aa3b, v161
	v_mul_f32_e32 v162, 0x3fb8aa3b, v162
	v_mul_f32_e32 v163, 0x3fb8aa3b, v163
	v_exp_f32_e32 v160, v160
	v_exp_f32_e32 v161, v161
	v_exp_f32_e32 v162, v162
	v_exp_f32_e32 v163, v163
	s_nop 0
	v_mul_f32_e32 v160, v8, v160
	v_mul_f32_e32 v161, v9, v161
	v_mul_f32_e32 v162, v10, v162
	v_mul_f32_e32 v163, v11, v163
	v_mul_f32_e32 v160, v160, v156
	v_mul_f32_e32 v161, v161, v157
	v_mul_f32_e32 v162, v162, v158
	v_mul_f32_e32 v163, v163, v159
	v_cndmask_b32_e64 v160, 0, v160, s[52:53]
	v_cndmask_b32_e64 v161, 0, v161, s[54:55]
	v_cndmask_b32_e64 v162, 0, v162, s[56:57]
	v_cndmask_b32_e64 v163, 0, v163, s[58:59]
	v_cvt_pk_bf16_f32 v164, v160, v161
	v_cvt_pk_bf16_f32 v165, v162, v163
	ds_write_b64 v189, v[164:165] offset:64
	s_cmp_lt_u32 s2, 3
	s_cbranch_scc1 .Lm3_h0_skip3
	ds_read_b128 v[152:155], v188 offset:2240
	ds_read_b128 v[156:159], v188 offset:192
	s_cmp_eq_u32 s2, 3
	s_cselect_b64 s[52:53], s[44:45], -1
	s_cselect_b64 s[54:55], s[46:47], -1
	s_cselect_b64 s[56:57], s[48:49], -1
	s_cselect_b64 s[58:59], s[50:51], -1
	s_waitcnt lgkmcnt(0)
	v_sub_f32_e32 v160, v206, v152
	v_sub_f32_e32 v161, v206, v153
	v_sub_f32_e32 v162, v206, v154
	v_sub_f32_e32 v163, v206, v155
	v_min_f32_e32 v160, 0, v160
	v_min_f32_e32 v161, 0, v161
	v_min_f32_e32 v162, 0, v162
	v_min_f32_e32 v163, 0, v163
	v_mul_f32_e32 v160, 0x3fb8aa3b, v160
	v_mul_f32_e32 v161, 0x3fb8aa3b, v161
	v_mul_f32_e32 v162, 0x3fb8aa3b, v162
	v_mul_f32_e32 v163, 0x3fb8aa3b, v163
	v_exp_f32_e32 v160, v160
	v_exp_f32_e32 v161, v161
	v_exp_f32_e32 v162, v162
	v_exp_f32_e32 v163, v163
	s_nop 0
	v_mul_f32_e32 v160, v12, v160
	v_mul_f32_e32 v161, v13, v161
	v_mul_f32_e32 v162, v14, v162
	v_mul_f32_e32 v163, v15, v163
	v_mul_f32_e32 v160, v160, v156
	v_mul_f32_e32 v161, v161, v157
	v_mul_f32_e32 v162, v162, v158
	v_mul_f32_e32 v163, v163, v159
	v_cndmask_b32_e64 v160, 0, v160, s[52:53]
	v_cndmask_b32_e64 v161, 0, v161, s[54:55]
	v_cndmask_b32_e64 v162, 0, v162, s[56:57]
	v_cndmask_b32_e64 v163, 0, v163, s[58:59]
	v_cvt_pk_bf16_f32 v164, v160, v161
	v_cvt_pk_bf16_f32 v165, v162, v163
	ds_write_b64 v189, v[164:165] offset:96
	s_cmp_lt_u32 s2, 4
	s_cbranch_scc1 .Lm3_h0_skip4
; DI unsigned short f2bf(float f) { return (unsigned short)(pk2(f, 0.f) & 0xffffu); }
; __global__ void __launch_bounds__(512, 2) fwd_megakernel(Args args) {
;     ...
;                         for (int st = 0; st < 8; ++st) {
;                             if (st <= (wave | 1)) {
;                                 const int sI = 16 * st + r16; const float acss = hacs[sI], dts = hdt[sI];
; #pragma unroll
;                                 for (int j = 0; j < 4; ++j) { const int l = 16 * wave + q4 * 4 + j; const float mv = (sI <= l) ? cbr[st][j] * __expf(fminf(acl[j] - acss, 0.f)) * dts : 0.f; Ms[l * 136 + sI] = f2bf(mv); }
;                             }
	ds_read_b128 v[152:155], v188 offset:2304
	ds_read_b128 v[156:159], v188 offset:256
	s_cmp_eq_u32 s2, 4
	s_cselect_b64 s[52:53], s[44:45], -1
	s_cselect_b64 s[54:55], s[46:47], -1
	s_cselect_b64 s[56:57], s[48:49], -1
	s_cselect_b64 s[58:59], s[50:51], -1
	s_waitcnt lgkmcnt(0)
	v_sub_f32_e32 v160, v206, v152
	v_sub_f32_e32 v161, v206, v153
	v_sub_f32_e32 v162, v206, v154
	v_sub_f32_e32 v163, v206, v155
	v_min_f32_e32 v160, 0, v160
	v_min_f32_e32 v161, 0, v161
	v_min_f32_e32 v162, 0, v162
	v_min_f32_e32 v163, 0, v163
	v_mul_f32_e32 v160, 0x3fb8aa3b, v160
	v_mul_f32_e32 v161, 0x3fb8aa3b, v161
	v_mul_f32_e32 v162, 0x3fb8aa3b, v162
	v_mul_f32_e32 v163, 0x3fb8aa3b, v163
	v_exp_f32_e32 v160, v160
	v_exp_f32_e32 v161, v161
	v_exp_f32_e32 v162, v162
	v_exp_f32_e32 v163, v163
	s_nop 0
	v_mul_f32_e32 v160, v16, v160
	v_mul_f32_e32 v161, v17, v161
	v_mul_f32_e32 v162, v18, v162
	v_mul_f32_e32 v163, v19, v163
	v_mul_f32_e32 v160, v160, v156
	v_mul_f32_e32 v161, v161, v157
	v_mul_f32_e32 v162, v162, v158
	v_mul_f32_e32 v163, v163, v159
	v_cndmask_b32_e64 v160, 0, v160, s[52:53]
	v_cndmask_b32_e64 v161, 0, v161, s[54:55]
	v_cndmask_b32_e64 v162, 0, v162, s[56:57]
	v_cndmask_b32_e64 v163, 0, v163, s[58:59]
	v_cvt_pk_bf16_f32 v164, v160, v161
	v_cvt_pk_bf16_f32 v165, v162, v163
	ds_write_b64 v189, v[164:165] offset:128
	s_cmp_lt_u32 s2, 5
	s_cbranch_scc1 .Lm3_h0_skip5
	ds_read_b128 v[152:155], v188 offset:2368
	ds_read_b128 v[156:159], v188 offset:320
	s_cmp_eq_u32 s2, 5
	s_cselect_b64 s[52:53], s[44:45], -1
	s_cselect_b64 s[54:55], s[46:47], -1
	s_cselect_b64 s[56:57], s[48:49], -1
	s_cselect_b64 s[58:59], s[50:51], -1
	s_waitcnt lgkmcnt(0)
	v_sub_f32_e32 v160, v206, v152
	v_sub_f32_e32 v161, v206, v153
	v_sub_f32_e32 v162, v206, v154
	v_sub_f32_e32 v163, v206, v155
	v_min_f32_e32 v160, 0, v160
	v_min_f32_e32 v161, 0, v161
	v_min_f32_e32 v162, 0, v162
	v_min_f32_e32 v163, 0, v163
	v_mul_f32_e32 v160, 0x3fb8aa3b, v160
	v_mul_f32_e32 v161, 0x3fb8aa3b, v161
	v_mul_f32_e32 v162, 0x3fb8aa3b, v162
	v_mul_f32_e32 v163, 0x3fb8aa3b, v163
	v_exp_f32_e32 v160, v160
	v_exp_f32_e32 v161, v161
	v_exp_f32_e32 v162, v162
	v_exp_f32_e32 v163, v163
	s_nop 0
	v_mul_f32_e32 v160, v20, v160
	v_mul_f32_e32 v161, v21, v161
	v_mul_f32_e32 v162, v22, v162
	v_mul_f32_e32 v163, v23, v163
	v_mul_f32_e32 v160, v160, v156
	v_mul_f32_e32 v161, v161, v157
	v_mul_f32_e32 v162, v162, v158
	v_mul_f32_e32 v163, v163, v159
	v_cndmask_b32_e64 v160, 0, v160, s[52:53]
	v_cndmask_b32_e64 v161, 0, v161, s[54:55]
	v_cndmask_b32_e64 v162, 0, v162, s[56:57]
	v_cndmask_b32_e64 v163, 0, v163, s[58:59]
	v_cvt_pk_bf16_f32 v164, v160, v161
	v_cvt_pk_bf16_f32 v165, v162, v163
	ds_write_b64 v189, v[164:165] offset:160
	s_cmp_lt_u32 s2, 6
	s_cbranch_scc1 .Lm3_h0_skip6
	ds_read_b128 v[152:155], v188 offset:2432
	ds_read_b128 v[156:159], v188 offset:384
	s_cmp_eq_u32 s2, 6
	s_cselect_b64 s[52:53], s[44:45], -1
	s_cselect_b64 s[54:55], s[46:47], -1
	s_cselect_b64 s[56:57], s[48:49], -1
	s_cselect_b64 s[58:59], s[50:51], -1
	s_waitcnt lgkmcnt(0)
	v_sub_f32_e32 v160, v206, v152
	v_sub_f32_e32 v161, v206, v153
	v_sub_f32_e32 v162, v206, v154
	v_sub_f32_e32 v163, v206, v155
	v_min_f32_e32 v160, 0, v160
	v_min_f32_e32 v161, 0, v161
	v_min_f32_e32 v162, 0, v162
	v_min_f32_e32 v163, 0, v163
	v_mul_f32_e32 v160, 0x3fb8aa3b, v160
	v_mul_f32_e32 v161, 0x3fb8aa3b, v161
	v_mul_f32_e32 v162, 0x3fb8aa3b, v162
	v_mul_f32_e32 v163, 0x3fb8aa3b, v163
	v_exp_f32_e32 v160, v160
	v_exp_f32_e32 v161, v161
	v_exp_f32_e32 v162, v162
	v_exp_f32_e32 v163, v163
	s_nop 0
	v_mul_f32_e32 v160, v24, v160
	v_mul_f32_e32 v161, v25, v161
	v_mul_f32_e32 v162, v26, v162
	v_mul_f32_e32 v163, v27, v163
	v_mul_f32_e32 v160, v160, v156
	v_mul_f32_e32 v161, v161, v157
	v_mul_f32_e32 v162, v162, v158
	v_mul_f32_e32 v163, v163, v159
	v_cndmask_b32_e64 v160, 0, v160, s[52:53]
	v_cndmask_b32_e64 v161, 0, v161, s[54:55]
	v_cndmask_b32_e64 v162, 0, v162, s[56:57]
	v_cndmask_b32_e64 v163, 0, v163, s[58:59]
	v_cvt_pk_bf16_f32 v164, v160, v161
	v_cvt_pk_bf16_f32 v165, v162, v163
	ds_write_b64 v189, v[164:165] offset:192
	s_cmp_lt_u32 s2, 7
	s_cbranch_scc1 .Lm3_h0_skip7
	ds_read_b128 v[152:155], v188 offset:2496
	ds_read_b128 v[156:159], v188 offset:448
	s_cmp_eq_u32 s2, 7
	s_cselect_b64 s[52:53], s[44:45], -1
	s_cselect_b64 s[54:55], s[46:47], -1
	s_cselect_b64 s[56:57], s[48:49], -1
	s_cselect_b64 s[58:59], s[50:51], -1
	s_waitcnt lgkmcnt(0)
	v_sub_f32_e32 v160, v206, v152
	v_sub_f32_e32 v161, v206, v153
	v_sub_f32_e32 v162, v206, v154
	v_sub_f32_e32 v163, v206, v155
	v_min_f32_e32 v160, 0, v160
	v_min_f32_e32 v161, 0, v161
	v_min_f32_e32 v162, 0, v162
	v_min_f32_e32 v163, 0, v163
	v_mul_f32_e32 v160, 0x3fb8aa3b, v160
	v_mul_f32_e32 v161, 0x3fb8aa3b, v161
	v_mul_f32_e32 v162, 0x3fb8aa3b, v162
	v_mul_f32_e32 v163, 0x3fb8aa3b, v163
	v_exp_f32_e32 v160, v160
	v_exp_f32_e32 v161, v161
	v_exp_f32_e32 v162, v162
	v_exp_f32_e32 v163, v163
	s_nop 0
	v_mul_f32_e32 v160, v28, v160
	v_mul_f32_e32 v161, v29, v161
	v_mul_f32_e32 v162, v30, v162
	v_mul_f32_e32 v163, v31, v163
	v_mul_f32_e32 v160, v160, v156
	v_mul_f32_e32 v161, v161, v157
	v_mul_f32_e32 v162, v162, v158
	v_mul_f32_e32 v163, v163, v159
	v_cndmask_b32_e64 v160, 0, v160, s[52:53]
	v_cndmask_b32_e64 v161, 0, v161, s[54:55]
	v_cndmask_b32_e64 v162, 0, v162, s[56:57]
	v_cndmask_b32_e64 v163, 0, v163, s[58:59]
	v_cvt_pk_bf16_f32 v164, v160, v161
	v_cvt_pk_bf16_f32 v165, v162, v163
	ds_write_b64 v189, v[164:165] offset:224
	s_branch .Lm3_h0_msdone
.Lm3_h0_skip1:
	s_cmp_eq_u32 s2, 0
	s_cbranch_scc0 .Lm3_h0_msdone
	ds_write_b64 v189, v[214:215] offset:32
	s_branch .Lm3_h0_msdone
.Lm3_h0_skip2:
	s_branch .Lm3_h0_msdone
.Lm3_h0_skip3:
	s_cmp_eq_u32 s2, 2
	s_cbranch_scc0 .Lm3_h0_msdone
	ds_write_b64 v189, v[214:215] offset:96
	s_branch .Lm3_h0_msdone

; DI unsigned short f2bf(float f) { return (unsigned short)(pk2(f, 0.f) & 0xffffu); }
; __global__ void __launch_bounds__(512, 2) fwd_megakernel(Args args) {
;     ...
;                         for (int st = 0; st < 8; ++st) {
;                             if (st <= (wave | 1)) {
;                                 const int sI = 16 * st + r16; const float acss = hacs[sI], dts = hdt[sI];
; #pragma unroll
;                                 for (int j = 0; j < 4; ++j) { const int l = 16 * wave + q4 * 4 + j; const float mv = (sI <= l) ? cbr[st][j] * __expf(fminf(acl[j] - acss, 0.f)) * dts : 0.f; Ms[l * 136 + sI] = f2bf(mv); }
;                             }
.Lm3_h0_skip5:
	s_cmp_eq_u32 s2, 4
	s_cbranch_scc0 .Lm3_h0_msdone
	ds_write_b64 v189, v[214:215] offset:160
	s_branch .Lm3_h0_msdone

; #define LAS __attribute__((address_space(3)))
; DI float bf2f(unsigned short b) { return __uint_as_float((unsigned)b << 16); }
; DI f32x4 mfma16(bf16x8 a, bf16x8 b, f32x4 c) { return __builtin_amdgcn_mfma_f32_16x16x32_bf16(a, b, c, 0, 0, 0); }
; __global__ void __launch_bounds__(512, 2) fwd_megakernel(Args args) {
;     ...
;                         f32x4 yo[4], yd[4];
; #pragma unroll
;                         for (int pt = 0; pt < 4; ++pt) { yo[pt] = (f32x4){0.f, 0.f, 0.f, 0.f}; yd[pt] = (f32x4){0.f, 0.f, 0.f, 0.f}; }
;                         const LAS bf16* xh = xT + hh * (64 * 136);
; #pragma unroll
;                         for (int ks = 0; ks < 4; ++ks) {
;                             if (2 * ks <= wave) {
;                                 const bf16x8 ma = lds_frag(Ms, lrow, 136, ks * 32 + q4 * 8);
; #pragma unroll
;                                 for (int pt = 0; pt < 4; ++pt) yd[pt] = mfma16(ma, lds_frag(xh, 16 * pt + r16, 136, ks * 32 + q4 * 8), yd[pt]);
;                             }
;                         }
; #pragma unroll
;                         for (int ks = 0; ks < 4; ++ks)
; #pragma unroll
;                             for (int pt = 0; pt < 4; ++pt) yo[pt] = mfma16(ca[ks], pvf[ks][pt], yo[pt]);
;                         const float Dh = args.in[11][layer * 8 + h];
; #pragma unroll
;                         for (int j = 0; j < 4; ++j) {
;                             const int l = 16 * wave + q4 * 4 + j; const size_t row = grow0 + l; const float ea = __expf(acl[j]); float ss = 0.f;
; #pragma unroll
;                             for (int pt = 0; pt < 4; ++pt) {
;                                 const int p = 16 * pt + r16;
;                                 const float y = yd[pt][j] + ea * yo[pt][j] + Dh * bf2f(xh[p * 136 + l]);
.Lm3_h0_skip7:
	s_cmp_eq_u32 s2, 6
	s_cbranch_scc0 .Lm3_h0_msdone
	ds_write_b64 v189, v[214:215] offset:224
	s_branch .Lm3_h0_msdone
.Lm3_h0_msdone:
	v_mul_f32_e32 v207, 0x3fb8aa3b, v206
	v_exp_f32_e32 v207, v207
	ds_read_u16 v136, v191 offset:0
	ds_read_u16 v137, v191 offset:272
	ds_read_u16 v138, v191 offset:544
	ds_read_u16 v139, v191 offset:816
	ds_read_u16 v140, v191 offset:4352
	ds_read_u16 v141, v191 offset:4624
	ds_read_u16 v142, v191 offset:4896
	ds_read_u16 v143, v191 offset:5168
	ds_read_u16 v144, v191 offset:8704
	ds_read_u16 v145, v191 offset:8976
	ds_read_u16 v146, v191 offset:9248
	ds_read_u16 v147, v191 offset:9520
	ds_read_u16 v148, v191 offset:13056
	ds_read_u16 v149, v191 offset:13328
	ds_read_u16 v150, v191 offset:13600
	ds_read_u16 v151, v191 offset:13872
	s_waitcnt vmcnt(0)
	v_mfma_f32_16x16x32_bf16 v[112:115], v[48:51], v[32:35], 0
	v_mfma_f32_16x16x32_bf16 v[116:119], v[52:55], v[32:35], 0
	v_mfma_f32_16x16x32_bf16 v[120:123], v[56:59], v[32:35], 0
	v_mfma_f32_16x16x32_bf16 v[124:127], v[60:63], v[32:35], 0
	v_mfma_f32_16x16x32_bf16 v[112:115], v[64:67], v[36:39], v[112:115]
	v_mfma_f32_16x16x32_bf16 v[116:119], v[68:71], v[36:39], v[116:119]
	v_mfma_f32_16x16x32_bf16 v[120:123], v[72:75], v[36:39], v[120:123]
	v_mfma_f32_16x16x32_bf16 v[124:127], v[76:79], v[36:39], v[124:127]
	v_mfma_f32_16x16x32_bf16 v[112:115], v[80:83], v[40:43], v[112:115]
	v_mfma_f32_16x16x32_bf16 v[116:119], v[84:87], v[40:43], v[116:119]
	v_mfma_f32_16x16x32_bf16 v[120:123], v[88:91], v[40:43], v[120:123]
	v_mfma_f32_16x16x32_bf16 v[124:127], v[92:95], v[40:43], v[124:127]
	v_mfma_f32_16x16x32_bf16 v[112:115], v[96:99], v[44:47], v[112:115]
	v_mfma_f32_16x16x32_bf16 v[116:119], v[100:103], v[44:47], v[116:119]
	v_mfma_f32_16x16x32_bf16 v[120:123], v[104:107], v[44:47], v[120:123]
	v_mfma_f32_16x16x32_bf16 v[124:127], v[108:111], v[44:47], v[124:127]
	s_add_u32 s8, s8, 0x4000
	s_addc_u32 s9, s9, 0
	s_add_u32 s10, s10, 0x80
	s_addc_u32 s11, s11, 0
	global_load_dwordx4 v[48:51], v180, s[8:9] offset:0
	global_load_dwordx4 v[52:55], v181, s[8:9] offset:0
	global_load_dwordx4 v[56:59], v182, s[8:9] offset:0
	global_load_dwordx4 v[60:63], v183, s[8:9] offset:0
	global_load_dwordx4 v[64:67], v180, s[8:9] offset:64
	global_load_dwordx4 v[68:71], v181, s[8:9] offset:64
	global_load_dwordx4 v[72:75], v182, s[8:9] offset:64
	global_load_dwordx4 v[76:79], v183, s[8:9] offset:64
	global_load_dwordx4 v[80:83], v180, s[8:9] offset:128
	global_load_dwordx4 v[84:87], v181, s[8:9] offset:128
	global_load_dwordx4 v[88:91], v182, s[8:9] offset:128
	global_load_dwordx4 v[92:95], v183, s[8:9] offset:128
	global_load_dwordx4 v[96:99], v180, s[8:9] offset:192
	global_load_dwordx4 v[100:103], v181, s[8:9] offset:192
	global_load_dwordx4 v[104:107], v182, s[8:9] offset:192
	global_load_dwordx4 v[108:111], v183, s[8:9] offset:192
	global_load_dwordx2 v[196:197], v184, s[10:11] offset:0
	global_load_dwordx2 v[198:199], v184, s[10:11] offset:32
	global_load_dwordx2 v[202:203], v184, s[10:11] offset:64
	global_load_dwordx2 v[204:205], v184, s[10:11] offset:96
	v_mul_f32_e32 v112, v207, v112
	v_mul_f32_e32 v113, v207, v113
	v_mul_f32_e32 v114, v207, v114
	v_mul_f32_e32 v115, v207, v115
	v_mul_f32_e32 v116, v207, v116
	v_mul_f32_e32 v117, v207, v117
	v_mul_f32_e32 v118, v207, v118
	v_mul_f32_e32 v119, v207, v119
	v_mul_f32_e32 v120, v207, v120
	v_mul_f32_e32 v121, v207, v121
	v_mul_f32_e32 v122, v207, v122
	v_mul_f32_e32 v123, v207, v123
	v_mul_f32_e32 v124, v207, v124
	v_mul_f32_e32 v125, v207, v125
	v_mul_f32_e32 v126, v207, v126
	v_mul_f32_e32 v127, v207, v127
	s_waitcnt lgkmcnt(0)
	ds_read_b128 v[160:163], v179 offset:34816
	ds_read_b128 v[164:167], v190 offset:0
	ds_read_b128 v[168:171], v190 offset:4352
	ds_read_b128 v[172:175], v190 offset:8704
	ds_read_b128 v[152:155], v190 offset:13056
	s_waitcnt lgkmcnt(0)
	v_mfma_f32_16x16x32_bf16 v[112:115], v[164:167], v[160:163], v[112:115]
	v_mfma_f32_16x16x32_bf16 v[116:119], v[168:171], v[160:163], v[116:119]
	v_mfma_f32_16x16x32_bf16 v[120:123], v[172:175], v[160:163], v[120:123]
	v_mfma_f32_16x16x32_bf16 v[124:127], v[152:155], v[160:163], v[124:127]
	s_cmp_lt_u32 s2, 2
	s_cbranch_scc1 .Lm3_h0_yddone
	ds_read_b128 v[160:163], v179 offset:34880
	ds_read_b128 v[164:167], v190 offset:64
	ds_read_b128 v[168:171], v190 offset:4416
	ds_read_b128 v[172:175], v190 offset:8768
	ds_read_b128 v[152:155], v190 offset:13120
	s_waitcnt lgkmcnt(0)
	v_mfma_f32_16x16x32_bf16 v[112:115], v[164:167], v[160:163], v[112:115]
	v_mfma_f32_16x16x32_bf16 v[116:119], v[168:171], v[160:163], v[116:119]
	v_mfma_f32_16x16x32_bf16 v[120:123], v[172:175], v[160:163], v[120:123]
	v_mfma_f32_16x16x32_bf16 v[124:127], v[152:155], v[160:163], v[124:127]
	s_cmp_lt_u32 s2, 4
	s_cbranch_scc1 .Lm3_h0_yddone
	ds_read_b128 v[160:163], v179 offset:34944
	ds_read_b128 v[164:167], v190 offset:128
	ds_read_b128 v[168:171], v190 offset:4480
	ds_read_b128 v[172:175], v190 offset:8832
	ds_read_b128 v[152:155], v190 offset:13184
	s_waitcnt lgkmcnt(0)
	v_mfma_f32_16x16x32_bf16 v[112:115], v[164:167], v[160:163], v[112:115]
	v_mfma_f32_16x16x32_bf16 v[116:119], v[168:171], v[160:163], v[116:119]
	v_mfma_f32_16x16x32_bf16 v[120:123], v[172:175], v[160:163], v[120:123]
	v_mfma_f32_16x16x32_bf16 v[124:127], v[152:155], v[160:163], v[124:127]
	s_cmp_lt_u32 s2, 6
	s_cbranch_scc1 .Lm3_h0_yddone
	ds_read_b128 v[160:163], v179 offset:35008
	ds_read_b128 v[164:167], v190 offset:192
	ds_read_b128 v[168:171], v190 offset:4544
	ds_read_b128 v[172:175], v190 offset:8896
	ds_read_b128 v[152:155], v190 offset:13248
	s_waitcnt lgkmcnt(0)
	v_mfma_f32_16x16x32_bf16 v[112:115], v[164:167], v[160:163], v[112:115]
	v_mfma_f32_16x16x32_bf16 v[116:119], v[168:171], v[160:163], v[116:119]
	v_mfma_f32_16x16x32_bf16 v[120:123], v[172:175], v[160:163], v[120:123]
	v_mfma_f32_16x16x32_bf16 v[124:127], v[152:155], v[160:163], v[124:127]
; DI float bf2f(unsigned short b) { return __uint_as_float((unsigned)b << 16); }
; DI unsigned short f2bf(float f) { return (unsigned short)(pk2(f, 0.f) & 0xffffu); }
; DI float silu_f(float x) { return x * fast_sigmoid(x); }
; DI float sum16(float v) { v += __shfl_xor(v, 1); v += __shfl_xor(v, 2); v += __shfl_xor(v, 4); v += __shfl_xor(v, 8); return v; }
; __global__ void __launch_bounds__(512, 2) fwd_megakernel(Args args) {
;     ...
;                         for (int j = 0; j < 4; ++j) {
;                             const int l = 16 * wave + q4 * 4 + j; const size_t row = grow0 + l; const float ea = __expf(acl[j]); float ss = 0.f;
; #pragma unroll
;                             for (int pt = 0; pt < 4; ++pt) {
;                                 const int p = 16 * pt + r16;
;                                 const float y = yd[pt][j] + ea * yo[pt][j] + Dh * bf2f(xh[p * 136 + l]);
;                                 const float o = y * silu_f(bf2f(zr[j][pt])); ss += o * o; Yg[row * DM + h * 64 + p] = f2bf(o);
;                             }
;                             ss = sum16(ss);
;                             if (r16 == 0) mss_g[((size_t)g2 * MTOK + row) * 4 + hh] = ss;
.Lm3_h0_yddone:
	s_nop 7
	s_nop 3
	v_lshlrev_b32_e32 v160, 16, v128
	v_and_b32_e32 v161, 0xffff0000, v128
	v_lshlrev_b32_e32 v162, 16, v129
	v_and_b32_e32 v163, 0xffff0000, v129
	v_lshlrev_b32_e32 v136, 16, v136
	v_lshlrev_b32_e32 v137, 16, v137
	v_lshlrev_b32_e32 v138, 16, v138
	v_lshlrev_b32_e32 v139, 16, v139
	v_fmac_f32_e32 v112, s36, v136
	v_fmac_f32_e32 v113, s36, v137
	v_fmac_f32_e32 v114, s36, v138
	v_fmac_f32_e32 v115, s36, v139
	v_mul_f32_e32 v164, 0xbfb8aa3b, v160
	v_mul_f32_e32 v165, 0xbfb8aa3b, v161
	v_mul_f32_e32 v166, 0xbfb8aa3b, v162
	v_mul_f32_e32 v167, 0xbfb8aa3b, v163
	v_exp_f32_e32 v164, v164
	v_exp_f32_e32 v165, v165
	v_exp_f32_e32 v166, v166
	v_exp_f32_e32 v167, v167
	s_nop 0
	v_add_f32_e32 v164, 1.0, v164
	v_add_f32_e32 v165, 1.0, v165
	v_add_f32_e32 v166, 1.0, v166
	v_add_f32_e32 v167, 1.0, v167
	v_rcp_f32_e32 v164, v164
	v_rcp_f32_e32 v165, v165
	v_rcp_f32_e32 v166, v166
	v_rcp_f32_e32 v167, v167
	s_nop 0
	v_mul_f32_e32 v164, v164, v160
	v_mul_f32_e32 v165, v165, v161
	v_mul_f32_e32 v166, v166, v162
	v_mul_f32_e32 v167, v167, v163
	v_mul_f32_e32 v164, v112, v164
	v_mul_f32_e32 v165, v113, v165
	v_mul_f32_e32 v166, v114, v166
	v_mul_f32_e32 v167, v115, v167
	v_mul_f32_e32 v208, v164, v164
	v_fmac_f32_e32 v208, v165, v165
	v_fmac_f32_e32 v208, v166, v166
	v_fmac_f32_e32 v208, v167, v167
	v_cvt_pk_bf16_f32 v168, v164, v165
	v_cvt_pk_bf16_f32 v169, v166, v167
	global_store_dwordx2 v185, v[168:169], s[12:13] offset:0
	v_lshlrev_b32_e32 v160, 16, v130
	v_and_b32_e32 v161, 0xffff0000, v130
	v_lshlrev_b32_e32 v162, 16, v131
	v_and_b32_e32 v163, 0xffff0000, v131
	v_lshlrev_b32_e32 v140, 16, v140
	v_lshlrev_b32_e32 v141, 16, v141
	v_lshlrev_b32_e32 v142, 16, v142
	v_lshlrev_b32_e32 v143, 16, v143
	v_fmac_f32_e32 v116, s36, v140
	v_fmac_f32_e32 v117, s36, v141
	v_fmac_f32_e32 v118, s36, v142
	v_fmac_f32_e32 v119, s36, v143
	v_mul_f32_e32 v164, 0xbfb8aa3b, v160
	v_mul_f32_e32 v165, 0xbfb8aa3b, v161
	v_mul_f32_e32 v166, 0xbfb8aa3b, v162
	v_mul_f32_e32 v167, 0xbfb8aa3b, v163
	v_exp_f32_e32 v164, v164
	v_exp_f32_e32 v165, v165
	v_exp_f32_e32 v166, v166
	v_exp_f32_e32 v167, v167
	s_nop 0
	v_add_f32_e32 v164, 1.0, v164
	v_add_f32_e32 v165, 1.0, v165
	v_add_f32_e32 v166, 1.0, v166
	v_add_f32_e32 v167, 1.0, v167
	v_rcp_f32_e32 v164, v164
	v_rcp_f32_e32 v165, v165
	v_rcp_f32_e32 v166, v166
	v_rcp_f32_e32 v167, v167
	s_nop 0
	v_mul_f32_e32 v164, v164, v160
	v_mul_f32_e32 v165, v165, v161
	v_mul_f32_e32 v166, v166, v162
	v_mul_f32_e32 v167, v167, v163
	v_mul_f32_e32 v164, v116, v164
	v_mul_f32_e32 v165, v117, v165
	v_mul_f32_e32 v166, v118, v166
	v_mul_f32_e32 v167, v119, v167
	v_fmac_f32_e32 v208, v164, v164
	v_fmac_f32_e32 v208, v165, v165
	v_fmac_f32_e32 v208, v166, v166
	v_fmac_f32_e32 v208, v167, v167
	v_cvt_pk_bf16_f32 v168, v164, v165
	v_cvt_pk_bf16_f32 v169, v166, v167
	global_store_dwordx2 v185, v[168:169], s[12:13] offset:32
	v_lshlrev_b32_e32 v160, 16, v132
	v_and_b32_e32 v161, 0xffff0000, v132
	v_lshlrev_b32_e32 v162, 16, v133
	v_and_b32_e32 v163, 0xffff0000, v133
	v_lshlrev_b32_e32 v144, 16, v144
	v_lshlrev_b32_e32 v145, 16, v145
	v_lshlrev_b32_e32 v146, 16, v146
	v_lshlrev_b32_e32 v147, 16, v147
	v_fmac_f32_e32 v120, s36, v144
	v_fmac_f32_e32 v121, s36, v145
	v_fmac_f32_e32 v122, s36, v146
	v_fmac_f32_e32 v123, s36, v147
	v_mul_f32_e32 v164, 0xbfb8aa3b, v160
	v_mul_f32_e32 v165, 0xbfb8aa3b, v161
	v_mul_f32_e32 v166, 0xbfb8aa3b, v162
	v_mul_f32_e32 v167, 0xbfb8aa3b, v163
	v_exp_f32_e32 v164, v164
	v_exp_f32_e32 v165, v165
	v_exp_f32_e32 v166, v166
	v_exp_f32_e32 v167, v167
	s_nop 0
	v_add_f32_e32 v164, 1.0, v164
	v_add_f32_e32 v165, 1.0, v165
	v_add_f32_e32 v166, 1.0, v166
	v_add_f32_e32 v167, 1.0, v167
	v_rcp_f32_e32 v164, v164
	v_rcp_f32_e32 v165, v165
	v_rcp_f32_e32 v166, v166
	v_rcp_f32_e32 v167, v167
	s_nop 0
	v_mul_f32_e32 v164, v164, v160
	v_mul_f32_e32 v165, v165, v161
	v_mul_f32_e32 v166, v166, v162
	v_mul_f32_e32 v167, v167, v163
	v_mul_f32_e32 v164, v120, v164
	v_mul_f32_e32 v165, v121, v165
	v_mul_f32_e32 v166, v122, v166
	v_mul_f32_e32 v167, v123, v167
	v_fmac_f32_e32 v208, v164, v164
	v_fmac_f32_e32 v208, v165, v165
	v_fmac_f32_e32 v208, v166, v166
	v_fmac_f32_e32 v208, v167, v167
	v_cvt_pk_bf16_f32 v168, v164, v165
	v_cvt_pk_bf16_f32 v169, v166, v167
	global_store_dwordx2 v185, v[168:169], s[12:13] offset:64
	v_lshlrev_b32_e32 v160, 16, v134
	v_and_b32_e32 v161, 0xffff0000, v134
	v_lshlrev_b32_e32 v162, 16, v135
	v_and_b32_e32 v163, 0xffff0000, v135
	v_lshlrev_b32_e32 v148, 16, v148
	v_lshlrev_b32_e32 v149, 16, v149
	v_lshlrev_b32_e32 v150, 16, v150
	v_lshlrev_b32_e32 v151, 16, v151
	v_fmac_f32_e32 v124, s36, v148
	v_fmac_f32_e32 v125, s36, v149
	v_fmac_f32_e32 v126, s36, v150
	v_fmac_f32_e32 v127, s36, v151
	v_mul_f32_e32 v164, 0xbfb8aa3b, v160
	v_mul_f32_e32 v165, 0xbfb8aa3b, v161
	v_mul_f32_e32 v166, 0xbfb8aa3b, v162
	v_mul_f32_e32 v167, 0xbfb8aa3b, v163
	v_exp_f32_e32 v164, v164
	v_exp_f32_e32 v165, v165
	v_exp_f32_e32 v166, v166
	v_exp_f32_e32 v167, v167
	s_nop 0
	v_add_f32_e32 v164, 1.0, v164
	v_add_f32_e32 v165, 1.0, v165
	v_add_f32_e32 v166, 1.0, v166
	v_add_f32_e32 v167, 1.0, v167
	v_rcp_f32_e32 v164, v164
	v_rcp_f32_e32 v165, v165
	v_rcp_f32_e32 v166, v166
	v_rcp_f32_e32 v167, v167
	s_nop 0
	v_mul_f32_e32 v164, v164, v160
	v_mul_f32_e32 v165, v165, v161
	v_mul_f32_e32 v166, v166, v162
	v_mul_f32_e32 v167, v167, v163
	v_mul_f32_e32 v164, v124, v164
	v_mul_f32_e32 v165, v125, v165
	v_mul_f32_e32 v166, v126, v166
	v_mul_f32_e32 v167, v127, v167
	v_fmac_f32_e32 v208, v164, v164
	v_fmac_f32_e32 v208, v165, v165
	v_fmac_f32_e32 v208, v166, v166
	v_fmac_f32_e32 v208, v167, v167
	v_cvt_pk_bf16_f32 v168, v164, v165
	v_cvt_pk_bf16_f32 v169, v166, v167
	global_store_dwordx2 v185, v[168:169], s[12:13] offset:96
	ds_bpermute_b32 v213, v211, v208
	s_waitcnt lgkmcnt(0)
; #define LAS __attribute__((address_space(3)))
; DI unsigned short f2bf(float f) { return (unsigned short)(pk2(f, 0.f) & 0xffffu); }
; DI float sum16(float v) { v += __shfl_xor(v, 1); v += __shfl_xor(v, 2); v += __shfl_xor(v, 4); v += __shfl_xor(v, 8); return v; }
; __global__ void __launch_bounds__(512, 2) fwd_megakernel(Args args) {
;     ...
;                         const LAS float* hdt = s_dt + hh * 128; const LAS float* hacs = s_acs + hh * 128;
;                         float acl[4];
; #pragma unroll
;                         for (int j = 0; j < 4; ++j) acl[j] = hacs[16 * wave + q4 * 4 + j];
; #pragma unroll
;                         for (int st = 0; st < 8; ++st) {
;                             if (st <= (wave | 1)) {
;                                 const int sI = 16 * st + r16; const float acss = hacs[sI], dts = hdt[sI];
; #pragma unroll
;                                 for (int j = 0; j < 4; ++j) { const int l = 16 * wave + q4 * 4 + j; const float mv = (sI <= l) ? cbr[st][j] * __expf(fminf(acl[j] - acss, 0.f)) * dts : 0.f; Ms[l * 136 + sI] = f2bf(mv); }
;                             }
;     ...
;                             ss = sum16(ss);
;                             if (r16 == 0) mss_g[((size_t)g2 * MTOK + row) * 4 + hh] = ss;
	v_add_f32_e32 v208, v208, v213
	ds_bpermute_b32 v213, v212, v208
	s_waitcnt lgkmcnt(0)
	v_add_f32_e32 v208, v208, v213
	s_mov_b64 exec, s[42:43]
	global_store_dword v186, v208, s[22:23]
	s_mov_b64 exec, -1
	s_add_u32 s12, s12, 0x80
	s_addc_u32 s13, s13, 0
	s_add_u32 s22, s22, 4
	s_addc_u32 s23, s23, 0
	v_add_u32_e32 v187, 0x200, v187
	v_add_u32_e32 v188, 0x200, v188
	v_add_u32_e32 v190, 0x4400, v190
	v_add_u32_e32 v191, 0x4400, v191
	ds_read_b32 v206, v187 offset:2048
	ds_read_b128 v[152:155], v188 offset:2048
	ds_read_b128 v[156:159], v188 offset:0
	s_cmp_eq_u32 s2, 0
	s_cselect_b64 s[52:53], s[44:45], -1
	s_cselect_b64 s[54:55], s[46:47], -1
	s_cselect_b64 s[56:57], s[48:49], -1
	s_cselect_b64 s[58:59], s[50:51], -1
	s_waitcnt lgkmcnt(0)
	v_sub_f32_e32 v160, v206, v152
	v_sub_f32_e32 v161, v206, v153
	v_sub_f32_e32 v162, v206, v154
	v_sub_f32_e32 v163, v206, v155
	v_min_f32_e32 v160, 0, v160
	v_min_f32_e32 v161, 0, v161
	v_min_f32_e32 v162, 0, v162
	v_min_f32_e32 v163, 0, v163
	v_mul_f32_e32 v160, 0x3fb8aa3b, v160
	v_mul_f32_e32 v161, 0x3fb8aa3b, v161
	v_mul_f32_e32 v162, 0x3fb8aa3b, v162
	v_mul_f32_e32 v163, 0x3fb8aa3b, v163
	v_exp_f32_e32 v160, v160
	v_exp_f32_e32 v161, v161
	v_exp_f32_e32 v162, v162
	v_exp_f32_e32 v163, v163
	s_nop 0
	v_mul_f32_e32 v160, v0, v160
	v_mul_f32_e32 v161, v1, v161
	v_mul_f32_e32 v162, v2, v162
	v_mul_f32_e32 v163, v3, v163
	v_mul_f32_e32 v160, v160, v156
	v_mul_f32_e32 v161, v161, v157
	v_mul_f32_e32 v162, v162, v158
	v_mul_f32_e32 v163, v163, v159
	v_cndmask_b32_e64 v160, 0, v160, s[52:53]
	v_cndmask_b32_e64 v161, 0, v161, s[54:55]
	v_cndmask_b32_e64 v162, 0, v162, s[56:57]
	v_cndmask_b32_e64 v163, 0, v163, s[58:59]
	v_cvt_pk_bf16_f32 v164, v160, v161
	v_cvt_pk_bf16_f32 v165, v162, v163
	ds_write_b64 v189, v[164:165] offset:0
	s_cmp_lt_u32 s2, 1
	s_cbranch_scc1 .Lm3_h1_skip1
	ds_read_b128 v[152:155], v188 offset:2112
	ds_read_b128 v[156:159], v188 offset:64
	s_cmp_eq_u32 s2, 1
	s_cselect_b64 s[52:53], s[44:45], -1
	s_cselect_b64 s[54:55], s[46:47], -1
	s_cselect_b64 s[56:57], s[48:49], -1
	s_cselect_b64 s[58:59], s[50:51], -1
	s_waitcnt lgkmcnt(0)
	v_sub_f32_e32 v160, v206, v152
	v_sub_f32_e32 v161, v206, v153
	v_sub_f32_e32 v162, v206, v154
	v_sub_f32_e32 v163, v206, v155
	v_min_f32_e32 v160, 0, v160
	v_min_f32_e32 v161, 0, v161
	v_min_f32_e32 v162, 0, v162
	v_min_f32_e32 v163, 0, v163
	v_mul_f32_e32 v160, 0x3fb8aa3b, v160
	v_mul_f32_e32 v161, 0x3fb8aa3b, v161
	v_mul_f32_e32 v162, 0x3fb8aa3b, v162
	v_mul_f32_e32 v163, 0x3fb8aa3b, v163
	v_exp_f32_e32 v160, v160
	v_exp_f32_e32 v161, v161
	v_exp_f32_e32 v162, v162
	v_exp_f32_e32 v163, v163
	s_nop 0
	v_mul_f32_e32 v160, v4, v160
	v_mul_f32_e32 v161, v5, v161
	v_mul_f32_e32 v162, v6, v162
	v_mul_f32_e32 v163, v7, v163
	v_mul_f32_e32 v160, v160, v156
	v_mul_f32_e32 v161, v161, v157
	v_mul_f32_e32 v162, v162, v158
	v_mul_f32_e32 v163, v163, v159
	v_cndmask_b32_e64 v160, 0, v160, s[52:53]
	v_cndmask_b32_e64 v161, 0, v161, s[54:55]
	v_cndmask_b32_e64 v162, 0, v162, s[56:57]
	v_cndmask_b32_e64 v163, 0, v163, s[58:59]
	v_cvt_pk_bf16_f32 v164, v160, v161
	v_cvt_pk_bf16_f32 v165, v162, v163
	ds_write_b64 v189, v[164:165] offset:32
	s_cmp_lt_u32 s2, 2
	s_cbranch_scc1 .Lm3_h1_skip2
	ds_read_b128 v[152:155], v188 offset:2176
	ds_read_b128 v[156:159], v188 offset:128
	s_cmp_eq_u32 s2, 2
	s_cselect_b64 s[52:53], s[44:45], -1
	s_cselect_b64 s[54:55], s[46:47], -1
	s_cselect_b64 s[56:57], s[48:49], -1
	s_cselect_b64 s[58:59], s[50:51], -1
	s_waitcnt lgkmcnt(0)
	v_sub_f32_e32 v160, v206, v152
	v_sub_f32_e32 v161, v206, v153
	v_sub_f32_e32 v162, v206, v154
	v_sub_f32_e32 v163, v206, v155
	v_min_f32_e32 v160, 0, v160
	v_min_f32_e32 v161, 0, v161
	v_min_f32_e32 v162, 0, v162
	v_min_f32_e32 v163, 0, v163
	v_mul_f32_e32 v160, 0x3fb8aa3b, v160
	v_mul_f32_e32 v161, 0x3fb8aa3b, v161
	v_mul_f32_e32 v162, 0x3fb8aa3b, v162
	v_mul_f32_e32 v163, 0x3fb8aa3b, v163
	v_exp_f32_e32 v160, v160
	v_exp_f32_e32 v161, v161
	v_exp_f32_e32 v162, v162
	v_exp_f32_e32 v163, v163
	s_nop 0
	v_mul_f32_e32 v160, v8, v160
	v_mul_f32_e32 v161, v9, v161
	v_mul_f32_e32 v162, v10, v162
	v_mul_f32_e32 v163, v11, v163
	v_mul_f32_e32 v160, v160, v156
	v_mul_f32_e32 v161, v161, v157
	v_mul_f32_e32 v162, v162, v158
	v_mul_f32_e32 v163, v163, v159
	v_cndmask_b32_e64 v160, 0, v160, s[52:53]
	v_cndmask_b32_e64 v161, 0, v161, s[54:55]
	v_cndmask_b32_e64 v162, 0, v162, s[56:57]
	v_cndmask_b32_e64 v163, 0, v163, s[58:59]
	v_cvt_pk_bf16_f32 v164, v160, v161
	v_cvt_pk_bf16_f32 v165, v162, v163
	ds_write_b64 v189, v[164:165] offset:64
	s_cmp_lt_u32 s2, 3
	s_cbranch_scc1 .Lm3_h1_skip3
	ds_read_b128 v[152:155], v188 offset:2240
	ds_read_b128 v[156:159], v188 offset:192
	s_cmp_eq_u32 s2, 3
	s_cselect_b64 s[52:53], s[44:45], -1
	s_cselect_b64 s[54:55], s[46:47], -1
	s_cselect_b64 s[56:57], s[48:49], -1
	s_cselect_b64 s[58:59], s[50:51], -1
	s_waitcnt lgkmcnt(0)
	v_sub_f32_e32 v160, v206, v152
	v_sub_f32_e32 v161, v206, v153
	v_sub_f32_e32 v162, v206, v154
	v_sub_f32_e32 v163, v206, v155
	v_min_f32_e32 v160, 0, v160
	v_min_f32_e32 v161, 0, v161
	v_min_f32_e32 v162, 0, v162
	v_min_f32_e32 v163, 0, v163
	v_mul_f32_e32 v160, 0x3fb8aa3b, v160
	v_mul_f32_e32 v161, 0x3fb8aa3b, v161
	v_mul_f32_e32 v162, 0x3fb8aa3b, v162
	v_mul_f32_e32 v163, 0x3fb8aa3b, v163
	v_exp_f32_e32 v160, v160
	v_exp_f32_e32 v161, v161
	v_exp_f32_e32 v162, v162
	v_exp_f32_e32 v163, v163
	s_nop 0
	v_mul_f32_e32 v160, v12, v160
	v_mul_f32_e32 v161, v13, v161
	v_mul_f32_e32 v162, v14, v162
	v_mul_f32_e32 v163, v15, v163
	v_mul_f32_e32 v160, v160, v156
	v_mul_f32_e32 v161, v161, v157
	v_mul_f32_e32 v162, v162, v158
	v_mul_f32_e32 v163, v163, v159
	v_cndmask_b32_e64 v160, 0, v160, s[52:53]
	v_cndmask_b32_e64 v161, 0, v161, s[54:55]
	v_cndmask_b32_e64 v162, 0, v162, s[56:57]
	v_cndmask_b32_e64 v163, 0, v163, s[58:59]
	v_cvt_pk_bf16_f32 v164, v160, v161
	v_cvt_pk_bf16_f32 v165, v162, v163
	ds_write_b64 v189, v[164:165] offset:96
	s_cmp_lt_u32 s2, 4
	s_cbranch_scc1 .Lm3_h1_skip4
; DI unsigned short f2bf(float f) { return (unsigned short)(pk2(f, 0.f) & 0xffffu); }
; __global__ void __launch_bounds__(512, 2) fwd_megakernel(Args args) {
;     ...
;                         for (int st = 0; st < 8; ++st) {
;                             if (st <= (wave | 1)) {
;                                 const int sI = 16 * st + r16; const float acss = hacs[sI], dts = hdt[sI];
; #pragma unroll
;                                 for (int j = 0; j < 4; ++j) { const int l = 16 * wave + q4 * 4 + j; const float mv = (sI <= l) ? cbr[st][j] * __expf(fminf(acl[j] - acss, 0.f)) * dts : 0.f; Ms[l * 136 + sI] = f2bf(mv); }
;                             }
	ds_read_b128 v[152:155], v188 offset:2304
	ds_read_b128 v[156:159], v188 offset:256
	s_cmp_eq_u32 s2, 4
	s_cselect_b64 s[52:53], s[44:45], -1
	s_cselect_b64 s[54:55], s[46:47], -1
	s_cselect_b64 s[56:57], s[48:49], -1
	s_cselect_b64 s[58:59], s[50:51], -1
	s_waitcnt lgkmcnt(0)
	v_sub_f32_e32 v160, v206, v152
	v_sub_f32_e32 v161, v206, v153
	v_sub_f32_e32 v162, v206, v154
	v_sub_f32_e32 v163, v206, v155
	v_min_f32_e32 v160, 0, v160
	v_min_f32_e32 v161, 0, v161
	v_min_f32_e32 v162, 0, v162
	v_min_f32_e32 v163, 0, v163
	v_mul_f32_e32 v160, 0x3fb8aa3b, v160
	v_mul_f32_e32 v161, 0x3fb8aa3b, v161
	v_mul_f32_e32 v162, 0x3fb8aa3b, v162
	v_mul_f32_e32 v163, 0x3fb8aa3b, v163
	v_exp_f32_e32 v160, v160
	v_exp_f32_e32 v161, v161
	v_exp_f32_e32 v162, v162
	v_exp_f32_e32 v163, v163
	s_nop 0
	v_mul_f32_e32 v160, v16, v160
	v_mul_f32_e32 v161, v17, v161
	v_mul_f32_e32 v162, v18, v162
	v_mul_f32_e32 v163, v19, v163
	v_mul_f32_e32 v160, v160, v156
	v_mul_f32_e32 v161, v161, v157
	v_mul_f32_e32 v162, v162, v158
	v_mul_f32_e32 v163, v163, v159
	v_cndmask_b32_e64 v160, 0, v160, s[52:53]
	v_cndmask_b32_e64 v161, 0, v161, s[54:55]
	v_cndmask_b32_e64 v162, 0, v162, s[56:57]
	v_cndmask_b32_e64 v163, 0, v163, s[58:59]
	v_cvt_pk_bf16_f32 v164, v160, v161
	v_cvt_pk_bf16_f32 v165, v162, v163
	ds_write_b64 v189, v[164:165] offset:128
	s_cmp_lt_u32 s2, 5
	s_cbranch_scc1 .Lm3_h1_skip5
	ds_read_b128 v[152:155], v188 offset:2368
	ds_read_b128 v[156:159], v188 offset:320
	s_cmp_eq_u32 s2, 5
	s_cselect_b64 s[52:53], s[44:45], -1
	s_cselect_b64 s[54:55], s[46:47], -1
	s_cselect_b64 s[56:57], s[48:49], -1
	s_cselect_b64 s[58:59], s[50:51], -1
	s_waitcnt lgkmcnt(0)
	v_sub_f32_e32 v160, v206, v152
	v_sub_f32_e32 v161, v206, v153
	v_sub_f32_e32 v162, v206, v154
	v_sub_f32_e32 v163, v206, v155
	v_min_f32_e32 v160, 0, v160
	v_min_f32_e32 v161, 0, v161
	v_min_f32_e32 v162, 0, v162
	v_min_f32_e32 v163, 0, v163
	v_mul_f32_e32 v160, 0x3fb8aa3b, v160
	v_mul_f32_e32 v161, 0x3fb8aa3b, v161
	v_mul_f32_e32 v162, 0x3fb8aa3b, v162
	v_mul_f32_e32 v163, 0x3fb8aa3b, v163
	v_exp_f32_e32 v160, v160
	v_exp_f32_e32 v161, v161
	v_exp_f32_e32 v162, v162
	v_exp_f32_e32 v163, v163
	s_nop 0
	v_mul_f32_e32 v160, v20, v160
	v_mul_f32_e32 v161, v21, v161
	v_mul_f32_e32 v162, v22, v162
	v_mul_f32_e32 v163, v23, v163
	v_mul_f32_e32 v160, v160, v156
	v_mul_f32_e32 v161, v161, v157
	v_mul_f32_e32 v162, v162, v158
	v_mul_f32_e32 v163, v163, v159
	v_cndmask_b32_e64 v160, 0, v160, s[52:53]
	v_cndmask_b32_e64 v161, 0, v161, s[54:55]
	v_cndmask_b32_e64 v162, 0, v162, s[56:57]
	v_cndmask_b32_e64 v163, 0, v163, s[58:59]
	v_cvt_pk_bf16_f32 v164, v160, v161
	v_cvt_pk_bf16_f32 v165, v162, v163
	ds_write_b64 v189, v[164:165] offset:160
	s_cmp_lt_u32 s2, 6
	s_cbranch_scc1 .Lm3_h1_skip6
	ds_read_b128 v[152:155], v188 offset:2432
	ds_read_b128 v[156:159], v188 offset:384
	s_cmp_eq_u32 s2, 6
	s_cselect_b64 s[52:53], s[44:45], -1
	s_cselect_b64 s[54:55], s[46:47], -1
	s_cselect_b64 s[56:57], s[48:49], -1
	s_cselect_b64 s[58:59], s[50:51], -1
	s_waitcnt lgkmcnt(0)
	v_sub_f32_e32 v160, v206, v152
	v_sub_f32_e32 v161, v206, v153
	v_sub_f32_e32 v162, v206, v154
	v_sub_f32_e32 v163, v206, v155
	v_min_f32_e32 v160, 0, v160
	v_min_f32_e32 v161, 0, v161
	v_min_f32_e32 v162, 0, v162
	v_min_f32_e32 v163, 0, v163
	v_mul_f32_e32 v160, 0x3fb8aa3b, v160
	v_mul_f32_e32 v161, 0x3fb8aa3b, v161
	v_mul_f32_e32 v162, 0x3fb8aa3b, v162
	v_mul_f32_e32 v163, 0x3fb8aa3b, v163
	v_exp_f32_e32 v160, v160
	v_exp_f32_e32 v161, v161
	v_exp_f32_e32 v162, v162
	v_exp_f32_e32 v163, v163
	s_nop 0
	v_mul_f32_e32 v160, v24, v160
	v_mul_f32_e32 v161, v25, v161
	v_mul_f32_e32 v162, v26, v162
	v_mul_f32_e32 v163, v27, v163
	v_mul_f32_e32 v160, v160, v156
	v_mul_f32_e32 v161, v161, v157
	v_mul_f32_e32 v162, v162, v158
	v_mul_f32_e32 v163, v163, v159
	v_cndmask_b32_e64 v160, 0, v160, s[52:53]
	v_cndmask_b32_e64 v161, 0, v161, s[54:55]
	v_cndmask_b32_e64 v162, 0, v162, s[56:57]
	v_cndmask_b32_e64 v163, 0, v163, s[58:59]
	v_cvt_pk_bf16_f32 v164, v160, v161
	v_cvt_pk_bf16_f32 v165, v162, v163
	ds_write_b64 v189, v[164:165] offset:192
	s_cmp_lt_u32 s2, 7
	s_cbranch_scc1 .Lm3_h1_skip7
	ds_read_b128 v[152:155], v188 offset:2496
	ds_read_b128 v[156:159], v188 offset:448
	s_cmp_eq_u32 s2, 7
	s_cselect_b64 s[52:53], s[44:45], -1
	s_cselect_b64 s[54:55], s[46:47], -1
	s_cselect_b64 s[56:57], s[48:49], -1
	s_cselect_b64 s[58:59], s[50:51], -1
	s_waitcnt lgkmcnt(0)
	v_sub_f32_e32 v160, v206, v152
	v_sub_f32_e32 v161, v206, v153
	v_sub_f32_e32 v162, v206, v154
	v_sub_f32_e32 v163, v206, v155
	v_min_f32_e32 v160, 0, v160
	v_min_f32_e32 v161, 0, v161
	v_min_f32_e32 v162, 0, v162
	v_min_f32_e32 v163, 0, v163
	v_mul_f32_e32 v160, 0x3fb8aa3b, v160
	v_mul_f32_e32 v161, 0x3fb8aa3b, v161
	v_mul_f32_e32 v162, 0x3fb8aa3b, v162
	v_mul_f32_e32 v163, 0x3fb8aa3b, v163
	v_exp_f32_e32 v160, v160
	v_exp_f32_e32 v161, v161
	v_exp_f32_e32 v162, v162
	v_exp_f32_e32 v163, v163
	s_nop 0
	v_mul_f32_e32 v160, v28, v160
	v_mul_f32_e32 v161, v29, v161
	v_mul_f32_e32 v162, v30, v162
	v_mul_f32_e32 v163, v31, v163
	v_mul_f32_e32 v160, v160, v156
	v_mul_f32_e32 v161, v161, v157
	v_mul_f32_e32 v162, v162, v158
	v_mul_f32_e32 v163, v163, v159
	v_cndmask_b32_e64 v160, 0, v160, s[52:53]
	v_cndmask_b32_e64 v161, 0, v161, s[54:55]
	v_cndmask_b32_e64 v162, 0, v162, s[56:57]
	v_cndmask_b32_e64 v163, 0, v163, s[58:59]
	v_cvt_pk_bf16_f32 v164, v160, v161
	v_cvt_pk_bf16_f32 v165, v162, v163
	ds_write_b64 v189, v[164:165] offset:224
	s_branch .Lm3_h1_msdone

; #define LAS __attribute__((address_space(3)))
; DI float bf2f(unsigned short b) { return __uint_as_float((unsigned)b << 16); }
; DI f32x4 mfma16(bf16x8 a, bf16x8 b, f32x4 c) { return __builtin_amdgcn_mfma_f32_16x16x32_bf16(a, b, c, 0, 0, 0); }
; __global__ void __launch_bounds__(512, 2) fwd_megakernel(Args args) {
;     ...
;                         f32x4 yo[4], yd[4];
; #pragma unroll
;                         for (int pt = 0; pt < 4; ++pt) { yo[pt] = (f32x4){0.f, 0.f, 0.f, 0.f}; yd[pt] = (f32x4){0.f, 0.f, 0.f, 0.f}; }
;                         const LAS bf16* xh = xT + hh * (64 * 136);
; #pragma unroll
;                         for (int ks = 0; ks < 4; ++ks) {
;                             if (2 * ks <= wave) {
;                                 const bf16x8 ma = lds_frag(Ms, lrow, 136, ks * 32 + q4 * 8);
; #pragma unroll
;                                 for (int pt = 0; pt < 4; ++pt) yd[pt] = mfma16(ma, lds_frag(xh, 16 * pt + r16, 136, ks * 32 + q4 * 8), yd[pt]);
;                             }
;                         }
; #pragma unroll
;                         for (int ks = 0; ks < 4; ++ks)
; #pragma unroll
;                             for (int pt = 0; pt < 4; ++pt) yo[pt] = mfma16(ca[ks], pvf[ks][pt], yo[pt]);
;                         const float Dh = args.in[11][layer * 8 + h];
; #pragma unroll
;                         for (int j = 0; j < 4; ++j) {
;                             const int l = 16 * wave + q4 * 4 + j; const size_t row = grow0 + l; const float ea = __expf(acl[j]); float ss = 0.f;
; #pragma unroll
;                             for (int pt = 0; pt < 4; ++pt) {
;                                 const int p = 16 * pt + r16;
;                                 const float y = yd[pt][j] + ea * yo[pt][j] + Dh * bf2f(xh[p * 136 + l]);
.Lm3_h1_msdone:
	v_mul_f32_e32 v207, 0x3fb8aa3b, v206
	v_exp_f32_e32 v207, v207
	ds_read_u16 v136, v191 offset:0
	ds_read_u16 v137, v191 offset:272
	ds_read_u16 v138, v191 offset:544
	ds_read_u16 v139, v191 offset:816
	ds_read_u16 v140, v191 offset:4352
	ds_read_u16 v141, v191 offset:4624
	ds_read_u16 v142, v191 offset:4896
	ds_read_u16 v143, v191 offset:5168
	ds_read_u16 v144, v191 offset:8704
	ds_read_u16 v145, v191 offset:8976
	ds_read_u16 v146, v191 offset:9248
	ds_read_u16 v147, v191 offset:9520
	ds_read_u16 v148, v191 offset:13056
	ds_read_u16 v149, v191 offset:13328
	ds_read_u16 v150, v191 offset:13600
	ds_read_u16 v151, v191 offset:13872
	s_waitcnt vmcnt(0)
	v_mfma_f32_16x16x32_bf16 v[112:115], v[48:51], v[32:35], 0
	v_mfma_f32_16x16x32_bf16 v[116:119], v[52:55], v[32:35], 0
	v_mfma_f32_16x16x32_bf16 v[120:123], v[56:59], v[32:35], 0
	v_mfma_f32_16x16x32_bf16 v[124:127], v[60:63], v[32:35], 0
	v_mfma_f32_16x16x32_bf16 v[112:115], v[64:67], v[36:39], v[112:115]
	v_mfma_f32_16x16x32_bf16 v[116:119], v[68:71], v[36:39], v[116:119]
	v_mfma_f32_16x16x32_bf16 v[120:123], v[72:75], v[36:39], v[120:123]
	v_mfma_f32_16x16x32_bf16 v[124:127], v[76:79], v[36:39], v[124:127]
	v_mfma_f32_16x16x32_bf16 v[112:115], v[80:83], v[40:43], v[112:115]
	v_mfma_f32_16x16x32_bf16 v[116:119], v[84:87], v[40:43], v[116:119]
	v_mfma_f32_16x16x32_bf16 v[120:123], v[88:91], v[40:43], v[120:123]
	v_mfma_f32_16x16x32_bf16 v[124:127], v[92:95], v[40:43], v[124:127]
	v_mfma_f32_16x16x32_bf16 v[112:115], v[96:99], v[44:47], v[112:115]
	v_mfma_f32_16x16x32_bf16 v[116:119], v[100:103], v[44:47], v[116:119]
	v_mfma_f32_16x16x32_bf16 v[120:123], v[104:107], v[44:47], v[120:123]
	v_mfma_f32_16x16x32_bf16 v[124:127], v[108:111], v[44:47], v[124:127]
	s_add_u32 s8, s8, 0x4000
	s_addc_u32 s9, s9, 0
	s_add_u32 s10, s10, 0x80
	s_addc_u32 s11, s11, 0
	global_load_dwordx4 v[48:51], v180, s[8:9] offset:0
	global_load_dwordx4 v[52:55], v181, s[8:9] offset:0
	global_load_dwordx4 v[56:59], v182, s[8:9] offset:0
	global_load_dwordx4 v[60:63], v183, s[8:9] offset:0
	global_load_dwordx4 v[64:67], v180, s[8:9] offset:64
	global_load_dwordx4 v[68:71], v181, s[8:9] offset:64
	global_load_dwordx4 v[72:75], v182, s[8:9] offset:64
	global_load_dwordx4 v[76:79], v183, s[8:9] offset:64
	global_load_dwordx4 v[80:83], v180, s[8:9] offset:128
	global_load_dwordx4 v[84:87], v181, s[8:9] offset:128
	global_load_dwordx4 v[88:91], v182, s[8:9] offset:128
	global_load_dwordx4 v[92:95], v183, s[8:9] offset:128
	global_load_dwordx4 v[96:99], v180, s[8:9] offset:192
	global_load_dwordx4 v[100:103], v181, s[8:9] offset:192
	global_load_dwordx4 v[104:107], v182, s[8:9] offset:192
	global_load_dwordx4 v[108:111], v183, s[8:9] offset:192
	global_load_dwordx2 v[128:129], v184, s[10:11] offset:0
	global_load_dwordx2 v[130:131], v184, s[10:11] offset:32
	global_load_dwordx2 v[132:133], v184, s[10:11] offset:64
	global_load_dwordx2 v[134:135], v184, s[10:11] offset:96
	v_mul_f32_e32 v112, v207, v112
	v_mul_f32_e32 v113, v207, v113
	v_mul_f32_e32 v114, v207, v114
	v_mul_f32_e32 v115, v207, v115
	v_mul_f32_e32 v116, v207, v116
	v_mul_f32_e32 v117, v207, v117
	v_mul_f32_e32 v118, v207, v118
	v_mul_f32_e32 v119, v207, v119
	v_mul_f32_e32 v120, v207, v120
	v_mul_f32_e32 v121, v207, v121
	v_mul_f32_e32 v122, v207, v122
	v_mul_f32_e32 v123, v207, v123
	v_mul_f32_e32 v124, v207, v124
	v_mul_f32_e32 v125, v207, v125
	v_mul_f32_e32 v126, v207, v126
	v_mul_f32_e32 v127, v207, v127
	s_waitcnt lgkmcnt(0)
	ds_read_b128 v[160:163], v179 offset:34816
	ds_read_b128 v[164:167], v190 offset:0
	ds_read_b128 v[168:171], v190 offset:4352
	ds_read_b128 v[172:175], v190 offset:8704
	ds_read_b128 v[152:155], v190 offset:13056
	s_waitcnt lgkmcnt(0)
	v_mfma_f32_16x16x32_bf16 v[112:115], v[164:167], v[160:163], v[112:115]
	v_mfma_f32_16x16x32_bf16 v[116:119], v[168:171], v[160:163], v[116:119]
	v_mfma_f32_16x16x32_bf16 v[120:123], v[172:175], v[160:163], v[120:123]
	v_mfma_f32_16x16x32_bf16 v[124:127], v[152:155], v[160:163], v[124:127]
	s_cmp_lt_u32 s2, 2
	s_cbranch_scc1 .Lm3_h1_yddone
	ds_read_b128 v[160:163], v179 offset:34880
	ds_read_b128 v[164:167], v190 offset:64
	ds_read_b128 v[168:171], v190 offset:4416
	ds_read_b128 v[172:175], v190 offset:8768
	ds_read_b128 v[152:155], v190 offset:13120
	s_waitcnt lgkmcnt(0)
	v_mfma_f32_16x16x32_bf16 v[112:115], v[164:167], v[160:163], v[112:115]
	v_mfma_f32_16x16x32_bf16 v[116:119], v[168:171], v[160:163], v[116:119]
	v_mfma_f32_16x16x32_bf16 v[120:123], v[172:175], v[160:163], v[120:123]
	v_mfma_f32_16x16x32_bf16 v[124:127], v[152:155], v[160:163], v[124:127]
	s_cmp_lt_u32 s2, 4
	s_cbranch_scc1 .Lm3_h1_yddone
	ds_read_b128 v[160:163], v179 offset:34944
	ds_read_b128 v[164:167], v190 offset:128
	ds_read_b128 v[168:171], v190 offset:4480
	ds_read_b128 v[172:175], v190 offset:8832
	ds_read_b128 v[152:155], v190 offset:13184
	s_waitcnt lgkmcnt(0)
	v_mfma_f32_16x16x32_bf16 v[112:115], v[164:167], v[160:163], v[112:115]
	v_mfma_f32_16x16x32_bf16 v[116:119], v[168:171], v[160:163], v[116:119]
	v_mfma_f32_16x16x32_bf16 v[120:123], v[172:175], v[160:163], v[120:123]
	v_mfma_f32_16x16x32_bf16 v[124:127], v[152:155], v[160:163], v[124:127]
	s_cmp_lt_u32 s2, 6
	s_cbranch_scc1 .Lm3_h1_yddone
	ds_read_b128 v[160:163], v179 offset:35008
	ds_read_b128 v[164:167], v190 offset:192
	ds_read_b128 v[168:171], v190 offset:4544
	ds_read_b128 v[172:175], v190 offset:8896
	ds_read_b128 v[152:155], v190 offset:13248
	s_waitcnt lgkmcnt(0)
	v_mfma_f32_16x16x32_bf16 v[112:115], v[164:167], v[160:163], v[112:115]
	v_mfma_f32_16x16x32_bf16 v[116:119], v[168:171], v[160:163], v[116:119]
	v_mfma_f32_16x16x32_bf16 v[120:123], v[172:175], v[160:163], v[120:123]
	v_mfma_f32_16x16x32_bf16 v[124:127], v[152:155], v[160:163], v[124:127]
; DI float bf2f(unsigned short b) { return __uint_as_float((unsigned)b << 16); }
; DI unsigned short f2bf(float f) { return (unsigned short)(pk2(f, 0.f) & 0xffffu); }
; DI float silu_f(float x) { return x * fast_sigmoid(x); }
; DI float sum16(float v) { v += __shfl_xor(v, 1); v += __shfl_xor(v, 2); v += __shfl_xor(v, 4); v += __shfl_xor(v, 8); return v; }
; __global__ void __launch_bounds__(512, 2) fwd_megakernel(Args args) {
;     ...
;                         for (int j = 0; j < 4; ++j) {
;                             const int l = 16 * wave + q4 * 4 + j; const size_t row = grow0 + l; const float ea = __expf(acl[j]); float ss = 0.f;
; #pragma unroll
;                             for (int pt = 0; pt < 4; ++pt) {
;                                 const int p = 16 * pt + r16;
;                                 const float y = yd[pt][j] + ea * yo[pt][j] + Dh * bf2f(xh[p * 136 + l]);
;                                 const float o = y * silu_f(bf2f(zr[j][pt])); ss += o * o; Yg[row * DM + h * 64 + p] = f2bf(o);
;                             }
;                             ss = sum16(ss);
;                             if (r16 == 0) mss_g[((size_t)g2 * MTOK + row) * 4 + hh] = ss;
.Lm3_h1_yddone:
	s_nop 7
	s_nop 3
	v_lshlrev_b32_e32 v160, 16, v196
	v_and_b32_e32 v161, 0xffff0000, v196
	v_lshlrev_b32_e32 v162, 16, v197
	v_and_b32_e32 v163, 0xffff0000, v197
	v_lshlrev_b32_e32 v136, 16, v136
	v_lshlrev_b32_e32 v137, 16, v137
	v_lshlrev_b32_e32 v138, 16, v138
	v_lshlrev_b32_e32 v139, 16, v139
	v_fmac_f32_e32 v112, s37, v136
	v_fmac_f32_e32 v113, s37, v137
	v_fmac_f32_e32 v114, s37, v138
	v_fmac_f32_e32 v115, s37, v139
	v_mul_f32_e32 v164, 0xbfb8aa3b, v160
	v_mul_f32_e32 v165, 0xbfb8aa3b, v161
	v_mul_f32_e32 v166, 0xbfb8aa3b, v162
	v_mul_f32_e32 v167, 0xbfb8aa3b, v163
	v_exp_f32_e32 v164, v164
	v_exp_f32_e32 v165, v165
	v_exp_f32_e32 v166, v166
	v_exp_f32_e32 v167, v167
	s_nop 0
	v_add_f32_e32 v164, 1.0, v164
	v_add_f32_e32 v165, 1.0, v165
	v_add_f32_e32 v166, 1.0, v166
	v_add_f32_e32 v167, 1.0, v167
	v_rcp_f32_e32 v164, v164
	v_rcp_f32_e32 v165, v165
	v_rcp_f32_e32 v166, v166
	v_rcp_f32_e32 v167, v167
	s_nop 0
	v_mul_f32_e32 v164, v164, v160
	v_mul_f32_e32 v165, v165, v161
	v_mul_f32_e32 v166, v166, v162
	v_mul_f32_e32 v167, v167, v163
	v_mul_f32_e32 v164, v112, v164
	v_mul_f32_e32 v165, v113, v165
	v_mul_f32_e32 v166, v114, v166
	v_mul_f32_e32 v167, v115, v167
	v_mul_f32_e32 v208, v164, v164
	v_fmac_f32_e32 v208, v165, v165
	v_fmac_f32_e32 v208, v166, v166
	v_fmac_f32_e32 v208, v167, v167
	v_cvt_pk_bf16_f32 v168, v164, v165
	v_cvt_pk_bf16_f32 v169, v166, v167
	global_store_dwordx2 v185, v[168:169], s[12:13] offset:0
	v_lshlrev_b32_e32 v160, 16, v198
	v_and_b32_e32 v161, 0xffff0000, v198
	v_lshlrev_b32_e32 v162, 16, v199
	v_and_b32_e32 v163, 0xffff0000, v199
	v_lshlrev_b32_e32 v140, 16, v140
	v_lshlrev_b32_e32 v141, 16, v141
	v_lshlrev_b32_e32 v142, 16, v142
	v_lshlrev_b32_e32 v143, 16, v143
	v_fmac_f32_e32 v116, s37, v140
	v_fmac_f32_e32 v117, s37, v141
	v_fmac_f32_e32 v118, s37, v142
	v_fmac_f32_e32 v119, s37, v143
	v_mul_f32_e32 v164, 0xbfb8aa3b, v160
	v_mul_f32_e32 v165, 0xbfb8aa3b, v161
	v_mul_f32_e32 v166, 0xbfb8aa3b, v162
	v_mul_f32_e32 v167, 0xbfb8aa3b, v163
	v_exp_f32_e32 v164, v164
	v_exp_f32_e32 v165, v165
	v_exp_f32_e32 v166, v166
	v_exp_f32_e32 v167, v167
	s_nop 0
	v_add_f32_e32 v164, 1.0, v164
	v_add_f32_e32 v165, 1.0, v165
	v_add_f32_e32 v166, 1.0, v166
	v_add_f32_e32 v167, 1.0, v167
	v_rcp_f32_e32 v164, v164
	v_rcp_f32_e32 v165, v165
	v_rcp_f32_e32 v166, v166
	v_rcp_f32_e32 v167, v167
	s_nop 0
	v_mul_f32_e32 v164, v164, v160
	v_mul_f32_e32 v165, v165, v161
	v_mul_f32_e32 v166, v166, v162
	v_mul_f32_e32 v167, v167, v163
	v_mul_f32_e32 v164, v116, v164
	v_mul_f32_e32 v165, v117, v165
	v_mul_f32_e32 v166, v118, v166
	v_mul_f32_e32 v167, v119, v167
	v_fmac_f32_e32 v208, v164, v164
	v_fmac_f32_e32 v208, v165, v165
	v_fmac_f32_e32 v208, v166, v166
	v_fmac_f32_e32 v208, v167, v167
	v_cvt_pk_bf16_f32 v168, v164, v165
	v_cvt_pk_bf16_f32 v169, v166, v167
	global_store_dwordx2 v185, v[168:169], s[12:13] offset:32
	v_lshlrev_b32_e32 v160, 16, v202
	v_and_b32_e32 v161, 0xffff0000, v202
	v_lshlrev_b32_e32 v162, 16, v203
	v_and_b32_e32 v163, 0xffff0000, v203
	v_lshlrev_b32_e32 v144, 16, v144
	v_lshlrev_b32_e32 v145, 16, v145
	v_lshlrev_b32_e32 v146, 16, v146
	v_lshlrev_b32_e32 v147, 16, v147
	v_fmac_f32_e32 v120, s37, v144
	v_fmac_f32_e32 v121, s37, v145
	v_fmac_f32_e32 v122, s37, v146
	v_fmac_f32_e32 v123, s37, v147
	v_mul_f32_e32 v164, 0xbfb8aa3b, v160
	v_mul_f32_e32 v165, 0xbfb8aa3b, v161
	v_mul_f32_e32 v166, 0xbfb8aa3b, v162
	v_mul_f32_e32 v167, 0xbfb8aa3b, v163
	v_exp_f32_e32 v164, v164
	v_exp_f32_e32 v165, v165
	v_exp_f32_e32 v166, v166
	v_exp_f32_e32 v167, v167
	s_nop 0
	v_add_f32_e32 v164, 1.0, v164
	v_add_f32_e32 v165, 1.0, v165
	v_add_f32_e32 v166, 1.0, v166
	v_add_f32_e32 v167, 1.0, v167
	v_rcp_f32_e32 v164, v164
	v_rcp_f32_e32 v165, v165
	v_rcp_f32_e32 v166, v166
	v_rcp_f32_e32 v167, v167
	s_nop 0
	v_mul_f32_e32 v164, v164, v160
	v_mul_f32_e32 v165, v165, v161
	v_mul_f32_e32 v166, v166, v162
	v_mul_f32_e32 v167, v167, v163
	v_mul_f32_e32 v164, v120, v164
	v_mul_f32_e32 v165, v121, v165
	v_mul_f32_e32 v166, v122, v166
	v_mul_f32_e32 v167, v123, v167
	v_fmac_f32_e32 v208, v164, v164
	v_fmac_f32_e32 v208, v165, v165
	v_fmac_f32_e32 v208, v166, v166
	v_fmac_f32_e32 v208, v167, v167
	v_cvt_pk_bf16_f32 v168, v164, v165
	v_cvt_pk_bf16_f32 v169, v166, v167
	global_store_dwordx2 v185, v[168:169], s[12:13] offset:64
	v_lshlrev_b32_e32 v160, 16, v204
	v_and_b32_e32 v161, 0xffff0000, v204
	v_lshlrev_b32_e32 v162, 16, v205
	v_and_b32_e32 v163, 0xffff0000, v205
	v_lshlrev_b32_e32 v148, 16, v148
	v_lshlrev_b32_e32 v149, 16, v149
	v_lshlrev_b32_e32 v150, 16, v150
	v_lshlrev_b32_e32 v151, 16, v151
	v_fmac_f32_e32 v124, s37, v148
	v_fmac_f32_e32 v125, s37, v149
	v_fmac_f32_e32 v126, s37, v150
	v_fmac_f32_e32 v127, s37, v151
	v_mul_f32_e32 v164, 0xbfb8aa3b, v160
	v_mul_f32_e32 v165, 0xbfb8aa3b, v161
	v_mul_f32_e32 v166, 0xbfb8aa3b, v162
	v_mul_f32_e32 v167, 0xbfb8aa3b, v163
	v_exp_f32_e32 v164, v164
	v_exp_f32_e32 v165, v165
	v_exp_f32_e32 v166, v166
	v_exp_f32_e32 v167, v167
	s_nop 0
	v_add_f32_e32 v164, 1.0, v164
	v_add_f32_e32 v165, 1.0, v165
	v_add_f32_e32 v166, 1.0, v166
	v_add_f32_e32 v167, 1.0, v167
	v_rcp_f32_e32 v164, v164
	v_rcp_f32_e32 v165, v165
	v_rcp_f32_e32 v166, v166
	v_rcp_f32_e32 v167, v167
	s_nop 0
	v_mul_f32_e32 v164, v164, v160
	v_mul_f32_e32 v165, v165, v161
	v_mul_f32_e32 v166, v166, v162
	v_mul_f32_e32 v167, v167, v163
	v_mul_f32_e32 v164, v124, v164
	v_mul_f32_e32 v165, v125, v165
	v_mul_f32_e32 v166, v126, v166
	v_mul_f32_e32 v167, v127, v167
	v_fmac_f32_e32 v208, v164, v164
	v_fmac_f32_e32 v208, v165, v165
	v_fmac_f32_e32 v208, v166, v166
	v_fmac_f32_e32 v208, v167, v167
	v_cvt_pk_bf16_f32 v168, v164, v165
	v_cvt_pk_bf16_f32 v169, v166, v167
	global_store_dwordx2 v185, v[168:169], s[12:13] offset:96
	ds_bpermute_b32 v213, v211, v208
	s_waitcnt lgkmcnt(0)
; #define LAS __attribute__((address_space(3)))
; DI unsigned short f2bf(float f) { return (unsigned short)(pk2(f, 0.f) & 0xffffu); }
; DI float sum16(float v) { v += __shfl_xor(v, 1); v += __shfl_xor(v, 2); v += __shfl_xor(v, 4); v += __shfl_xor(v, 8); return v; }
; __global__ void __launch_bounds__(512, 2) fwd_megakernel(Args args) {
;     ...
;                         const LAS float* hdt = s_dt + hh * 128; const LAS float* hacs = s_acs + hh * 128;
;                         float acl[4];
; #pragma unroll
;                         for (int j = 0; j < 4; ++j) acl[j] = hacs[16 * wave + q4 * 4 + j];
; #pragma unroll
;                         for (int st = 0; st < 8; ++st) {
;                             if (st <= (wave | 1)) {
;                                 const int sI = 16 * st + r16; const float acss = hacs[sI], dts = hdt[sI];
; #pragma unroll
;                                 for (int j = 0; j < 4; ++j) { const int l = 16 * wave + q4 * 4 + j; const float mv = (sI <= l) ? cbr[st][j] * __expf(fminf(acl[j] - acss, 0.f)) * dts : 0.f; Ms[l * 136 + sI] = f2bf(mv); }
;                             }
;     ...
;                             ss = sum16(ss);
;                             if (r16 == 0) mss_g[((size_t)g2 * MTOK + row) * 4 + hh] = ss;
	v_add_f32_e32 v208, v208, v213
	ds_bpermute_b32 v213, v212, v208
	s_waitcnt lgkmcnt(0)
	v_add_f32_e32 v208, v208, v213
	s_mov_b64 exec, s[42:43]
	global_store_dword v186, v208, s[22:23]
	s_mov_b64 exec, -1
	s_add_u32 s12, s12, 0x80
	s_addc_u32 s13, s13, 0
	s_add_u32 s22, s22, 4
	s_addc_u32 s23, s23, 0
	v_add_u32_e32 v187, 0x200, v187
	v_add_u32_e32 v188, 0x200, v188
	v_add_u32_e32 v190, 0x4400, v190
	v_add_u32_e32 v191, 0x4400, v191
	ds_read_b32 v206, v187 offset:2048
	ds_read_b128 v[152:155], v188 offset:2048
	ds_read_b128 v[156:159], v188 offset:0
	s_cmp_eq_u32 s2, 0
	s_cselect_b64 s[52:53], s[44:45], -1
	s_cselect_b64 s[54:55], s[46:47], -1
	s_cselect_b64 s[56:57], s[48:49], -1
	s_cselect_b64 s[58:59], s[50:51], -1
	s_waitcnt lgkmcnt(0)
	v_sub_f32_e32 v160, v206, v152
	v_sub_f32_e32 v161, v206, v153
	v_sub_f32_e32 v162, v206, v154
	v_sub_f32_e32 v163, v206, v155
	v_min_f32_e32 v160, 0, v160
	v_min_f32_e32 v161, 0, v161
	v_min_f32_e32 v162, 0, v162
	v_min_f32_e32 v163, 0, v163
	v_mul_f32_e32 v160, 0x3fb8aa3b, v160
	v_mul_f32_e32 v161, 0x3fb8aa3b, v161
	v_mul_f32_e32 v162, 0x3fb8aa3b, v162
	v_mul_f32_e32 v163, 0x3fb8aa3b, v163
	v_exp_f32_e32 v160, v160
	v_exp_f32_e32 v161, v161
	v_exp_f32_e32 v162, v162
	v_exp_f32_e32 v163, v163
	s_nop 0
	v_mul_f32_e32 v160, v0, v160
	v_mul_f32_e32 v161, v1, v161
	v_mul_f32_e32 v162, v2, v162
	v_mul_f32_e32 v163, v3, v163
	v_mul_f32_e32 v160, v160, v156
	v_mul_f32_e32 v161, v161, v157
	v_mul_f32_e32 v162, v162, v158
	v_mul_f32_e32 v163, v163, v159
	v_cndmask_b32_e64 v160, 0, v160, s[52:53]
	v_cndmask_b32_e64 v161, 0, v161, s[54:55]
	v_cndmask_b32_e64 v162, 0, v162, s[56:57]
	v_cndmask_b32_e64 v163, 0, v163, s[58:59]
	v_cvt_pk_bf16_f32 v164, v160, v161
	v_cvt_pk_bf16_f32 v165, v162, v163
	ds_write_b64 v189, v[164:165] offset:0
	s_cmp_lt_u32 s2, 1
	s_cbranch_scc1 .Lm3_h2_skip1
	ds_read_b128 v[152:155], v188 offset:2112
	ds_read_b128 v[156:159], v188 offset:64
	s_cmp_eq_u32 s2, 1
	s_cselect_b64 s[52:53], s[44:45], -1
	s_cselect_b64 s[54:55], s[46:47], -1
	s_cselect_b64 s[56:57], s[48:49], -1
	s_cselect_b64 s[58:59], s[50:51], -1
	s_waitcnt lgkmcnt(0)
	v_sub_f32_e32 v160, v206, v152
	v_sub_f32_e32 v161, v206, v153
	v_sub_f32_e32 v162, v206, v154
	v_sub_f32_e32 v163, v206, v155
	v_min_f32_e32 v160, 0, v160
	v_min_f32_e32 v161, 0, v161
	v_min_f32_e32 v162, 0, v162
	v_min_f32_e32 v163, 0, v163
	v_mul_f32_e32 v160, 0x3fb8aa3b, v160
	v_mul_f32_e32 v161, 0x3fb8aa3b, v161
	v_mul_f32_e32 v162, 0x3fb8aa3b, v162
	v_mul_f32_e32 v163, 0x3fb8aa3b, v163
	v_exp_f32_e32 v160, v160
	v_exp_f32_e32 v161, v161
	v_exp_f32_e32 v162, v162
	v_exp_f32_e32 v163, v163
	s_nop 0
	v_mul_f32_e32 v160, v4, v160
	v_mul_f32_e32 v161, v5, v161
	v_mul_f32_e32 v162, v6, v162
	v_mul_f32_e32 v163, v7, v163
	v_mul_f32_e32 v160, v160, v156
	v_mul_f32_e32 v161, v161, v157
	v_mul_f32_e32 v162, v162, v158
	v_mul_f32_e32 v163, v163, v159
	v_cndmask_b32_e64 v160, 0, v160, s[52:53]
	v_cndmask_b32_e64 v161, 0, v161, s[54:55]
	v_cndmask_b32_e64 v162, 0, v162, s[56:57]
	v_cndmask_b32_e64 v163, 0, v163, s[58:59]
	v_cvt_pk_bf16_f32 v164, v160, v161
	v_cvt_pk_bf16_f32 v165, v162, v163
	ds_write_b64 v189, v[164:165] offset:32
	s_cmp_lt_u32 s2, 2
	s_cbranch_scc1 .Lm3_h2_skip2
	ds_read_b128 v[152:155], v188 offset:2176
	ds_read_b128 v[156:159], v188 offset:128
	s_cmp_eq_u32 s2, 2
	s_cselect_b64 s[52:53], s[44:45], -1
	s_cselect_b64 s[54:55], s[46:47], -1
	s_cselect_b64 s[56:57], s[48:49], -1
	s_cselect_b64 s[58:59], s[50:51], -1
	s_waitcnt lgkmcnt(0)
	v_sub_f32_e32 v160, v206, v152
	v_sub_f32_e32 v161, v206, v153
	v_sub_f32_e32 v162, v206, v154
	v_sub_f32_e32 v163, v206, v155
	v_min_f32_e32 v160, 0, v160
	v_min_f32_e32 v161, 0, v161
	v_min_f32_e32 v162, 0, v162
	v_min_f32_e32 v163, 0, v163
	v_mul_f32_e32 v160, 0x3fb8aa3b, v160
	v_mul_f32_e32 v161, 0x3fb8aa3b, v161
	v_mul_f32_e32 v162, 0x3fb8aa3b, v162
	v_mul_f32_e32 v163, 0x3fb8aa3b, v163
	v_exp_f32_e32 v160, v160
	v_exp_f32_e32 v161, v161
	v_exp_f32_e32 v162, v162
	v_exp_f32_e32 v163, v163
	s_nop 0
	v_mul_f32_e32 v160, v8, v160
	v_mul_f32_e32 v161, v9, v161
	v_mul_f32_e32 v162, v10, v162
	v_mul_f32_e32 v163, v11, v163
	v_mul_f32_e32 v160, v160, v156
	v_mul_f32_e32 v161, v161, v157
	v_mul_f32_e32 v162, v162, v158
	v_mul_f32_e32 v163, v163, v159
	v_cndmask_b32_e64 v160, 0, v160, s[52:53]
	v_cndmask_b32_e64 v161, 0, v161, s[54:55]
	v_cndmask_b32_e64 v162, 0, v162, s[56:57]
	v_cndmask_b32_e64 v163, 0, v163, s[58:59]
	v_cvt_pk_bf16_f32 v164, v160, v161
	v_cvt_pk_bf16_f32 v165, v162, v163
	ds_write_b64 v189, v[164:165] offset:64
	s_cmp_lt_u32 s2, 3
	s_cbranch_scc1 .Lm3_h2_skip3
	ds_read_b128 v[152:155], v188 offset:2240
	ds_read_b128 v[156:159], v188 offset:192
	s_cmp_eq_u32 s2, 3
	s_cselect_b64 s[52:53], s[44:45], -1
	s_cselect_b64 s[54:55], s[46:47], -1
	s_cselect_b64 s[56:57], s[48:49], -1
	s_cselect_b64 s[58:59], s[50:51], -1
	s_waitcnt lgkmcnt(0)
	v_sub_f32_e32 v160, v206, v152
	v_sub_f32_e32 v161, v206, v153
	v_sub_f32_e32 v162, v206, v154
	v_sub_f32_e32 v163, v206, v155
	v_min_f32_e32 v160, 0, v160
	v_min_f32_e32 v161, 0, v161
	v_min_f32_e32 v162, 0, v162
	v_min_f32_e32 v163, 0, v163
	v_mul_f32_e32 v160, 0x3fb8aa3b, v160
	v_mul_f32_e32 v161, 0x3fb8aa3b, v161
	v_mul_f32_e32 v162, 0x3fb8aa3b, v162
	v_mul_f32_e32 v163, 0x3fb8aa3b, v163
	v_exp_f32_e32 v160, v160
	v_exp_f32_e32 v161, v161
	v_exp_f32_e32 v162, v162
	v_exp_f32_e32 v163, v163
	s_nop 0
	v_mul_f32_e32 v160, v12, v160
	v_mul_f32_e32 v161, v13, v161
	v_mul_f32_e32 v162, v14, v162
	v_mul_f32_e32 v163, v15, v163
	v_mul_f32_e32 v160, v160, v156
	v_mul_f32_e32 v161, v161, v157
	v_mul_f32_e32 v162, v162, v158
	v_mul_f32_e32 v163, v163, v159
	v_cndmask_b32_e64 v160, 0, v160, s[52:53]
	v_cndmask_b32_e64 v161, 0, v161, s[54:55]
	v_cndmask_b32_e64 v162, 0, v162, s[56:57]
	v_cndmask_b32_e64 v163, 0, v163, s[58:59]
	v_cvt_pk_bf16_f32 v164, v160, v161
	v_cvt_pk_bf16_f32 v165, v162, v163
	ds_write_b64 v189, v[164:165] offset:96
	s_cmp_lt_u32 s2, 4
	s_cbranch_scc1 .Lm3_h2_skip4
; DI unsigned short f2bf(float f) { return (unsigned short)(pk2(f, 0.f) & 0xffffu); }
; __global__ void __launch_bounds__(512, 2) fwd_megakernel(Args args) {
;     ...
;                         for (int st = 0; st < 8; ++st) {
;                             if (st <= (wave | 1)) {
;                                 const int sI = 16 * st + r16; const float acss = hacs[sI], dts = hdt[sI];
; #pragma unroll
;                                 for (int j = 0; j < 4; ++j) { const int l = 16 * wave + q4 * 4 + j; const float mv = (sI <= l) ? cbr[st][j] * __expf(fminf(acl[j] - acss, 0.f)) * dts : 0.f; Ms[l * 136 + sI] = f2bf(mv); }
;                             }
	ds_read_b128 v[152:155], v188 offset:2304
	ds_read_b128 v[156:159], v188 offset:256
	s_cmp_eq_u32 s2, 4
	s_cselect_b64 s[52:53], s[44:45], -1
	s_cselect_b64 s[54:55], s[46:47], -1
	s_cselect_b64 s[56:57], s[48:49], -1
	s_cselect_b64 s[58:59], s[50:51], -1
	s_waitcnt lgkmcnt(0)
	v_sub_f32_e32 v160, v206, v152
	v_sub_f32_e32 v161, v206, v153
	v_sub_f32_e32 v162, v206, v154
	v_sub_f32_e32 v163, v206, v155
	v_min_f32_e32 v160, 0, v160
	v_min_f32_e32 v161, 0, v161
	v_min_f32_e32 v162, 0, v162
	v_min_f32_e32 v163, 0, v163
	v_mul_f32_e32 v160, 0x3fb8aa3b, v160
	v_mul_f32_e32 v161, 0x3fb8aa3b, v161
	v_mul_f32_e32 v162, 0x3fb8aa3b, v162
	v_mul_f32_e32 v163, 0x3fb8aa3b, v163
	v_exp_f32_e32 v160, v160
	v_exp_f32_e32 v161, v161
	v_exp_f32_e32 v162, v162
	v_exp_f32_e32 v163, v163
	s_nop 0
	v_mul_f32_e32 v160, v16, v160
	v_mul_f32_e32 v161, v17, v161
	v_mul_f32_e32 v162, v18, v162
	v_mul_f32_e32 v163, v19, v163
	v_mul_f32_e32 v160, v160, v156
	v_mul_f32_e32 v161, v161, v157
	v_mul_f32_e32 v162, v162, v158
	v_mul_f32_e32 v163, v163, v159
	v_cndmask_b32_e64 v160, 0, v160, s[52:53]
	v_cndmask_b32_e64 v161, 0, v161, s[54:55]
	v_cndmask_b32_e64 v162, 0, v162, s[56:57]
	v_cndmask_b32_e64 v163, 0, v163, s[58:59]
	v_cvt_pk_bf16_f32 v164, v160, v161
	v_cvt_pk_bf16_f32 v165, v162, v163
	ds_write_b64 v189, v[164:165] offset:128
	s_cmp_lt_u32 s2, 5
	s_cbranch_scc1 .Lm3_h2_skip5
	ds_read_b128 v[152:155], v188 offset:2368
	ds_read_b128 v[156:159], v188 offset:320
	s_cmp_eq_u32 s2, 5
	s_cselect_b64 s[52:53], s[44:45], -1
	s_cselect_b64 s[54:55], s[46:47], -1
	s_cselect_b64 s[56:57], s[48:49], -1
	s_cselect_b64 s[58:59], s[50:51], -1
	s_waitcnt lgkmcnt(0)
	v_sub_f32_e32 v160, v206, v152
	v_sub_f32_e32 v161, v206, v153
	v_sub_f32_e32 v162, v206, v154
	v_sub_f32_e32 v163, v206, v155
	v_min_f32_e32 v160, 0, v160
	v_min_f32_e32 v161, 0, v161
	v_min_f32_e32 v162, 0, v162
	v_min_f32_e32 v163, 0, v163
	v_mul_f32_e32 v160, 0x3fb8aa3b, v160
	v_mul_f32_e32 v161, 0x3fb8aa3b, v161
	v_mul_f32_e32 v162, 0x3fb8aa3b, v162
	v_mul_f32_e32 v163, 0x3fb8aa3b, v163
	v_exp_f32_e32 v160, v160
	v_exp_f32_e32 v161, v161
	v_exp_f32_e32 v162, v162
	v_exp_f32_e32 v163, v163
	s_nop 0
	v_mul_f32_e32 v160, v20, v160
	v_mul_f32_e32 v161, v21, v161
	v_mul_f32_e32 v162, v22, v162
	v_mul_f32_e32 v163, v23, v163
	v_mul_f32_e32 v160, v160, v156
	v_mul_f32_e32 v161, v161, v157
	v_mul_f32_e32 v162, v162, v158
	v_mul_f32_e32 v163, v163, v159
	v_cndmask_b32_e64 v160, 0, v160, s[52:53]
	v_cndmask_b32_e64 v161, 0, v161, s[54:55]
	v_cndmask_b32_e64 v162, 0, v162, s[56:57]
	v_cndmask_b32_e64 v163, 0, v163, s[58:59]
	v_cvt_pk_bf16_f32 v164, v160, v161
	v_cvt_pk_bf16_f32 v165, v162, v163
	ds_write_b64 v189, v[164:165] offset:160
	s_cmp_lt_u32 s2, 6
	s_cbranch_scc1 .Lm3_h2_skip6
	ds_read_b128 v[152:155], v188 offset:2432
	ds_read_b128 v[156:159], v188 offset:384
	s_cmp_eq_u32 s2, 6
	s_cselect_b64 s[52:53], s[44:45], -1
	s_cselect_b64 s[54:55], s[46:47], -1
	s_cselect_b64 s[56:57], s[48:49], -1
	s_cselect_b64 s[58:59], s[50:51], -1
	s_waitcnt lgkmcnt(0)
	v_sub_f32_e32 v160, v206, v152
	v_sub_f32_e32 v161, v206, v153
	v_sub_f32_e32 v162, v206, v154
	v_sub_f32_e32 v163, v206, v155
	v_min_f32_e32 v160, 0, v160
	v_min_f32_e32 v161, 0, v161
	v_min_f32_e32 v162, 0, v162
	v_min_f32_e32 v163, 0, v163
	v_mul_f32_e32 v160, 0x3fb8aa3b, v160
	v_mul_f32_e32 v161, 0x3fb8aa3b, v161
	v_mul_f32_e32 v162, 0x3fb8aa3b, v162
	v_mul_f32_e32 v163, 0x3fb8aa3b, v163
	v_exp_f32_e32 v160, v160
	v_exp_f32_e32 v161, v161
	v_exp_f32_e32 v162, v162
	v_exp_f32_e32 v163, v163
	s_nop 0
	v_mul_f32_e32 v160, v24, v160
	v_mul_f32_e32 v161, v25, v161
	v_mul_f32_e32 v162, v26, v162
	v_mul_f32_e32 v163, v27, v163
	v_mul_f32_e32 v160, v160, v156
	v_mul_f32_e32 v161, v161, v157
	v_mul_f32_e32 v162, v162, v158
	v_mul_f32_e32 v163, v163, v159
	v_cndmask_b32_e64 v160, 0, v160, s[52:53]
	v_cndmask_b32_e64 v161, 0, v161, s[54:55]
	v_cndmask_b32_e64 v162, 0, v162, s[56:57]
	v_cndmask_b32_e64 v163, 0, v163, s[58:59]
	v_cvt_pk_bf16_f32 v164, v160, v161
	v_cvt_pk_bf16_f32 v165, v162, v163
	ds_write_b64 v189, v[164:165] offset:192
	s_cmp_lt_u32 s2, 7
	s_cbranch_scc1 .Lm3_h2_skip7
	ds_read_b128 v[152:155], v188 offset:2496
	ds_read_b128 v[156:159], v188 offset:448
	s_cmp_eq_u32 s2, 7
	s_cselect_b64 s[52:53], s[44:45], -1
	s_cselect_b64 s[54:55], s[46:47], -1
	s_cselect_b64 s[56:57], s[48:49], -1
	s_cselect_b64 s[58:59], s[50:51], -1
	s_waitcnt lgkmcnt(0)
	v_sub_f32_e32 v160, v206, v152
	v_sub_f32_e32 v161, v206, v153
	v_sub_f32_e32 v162, v206, v154
	v_sub_f32_e32 v163, v206, v155
	v_min_f32_e32 v160, 0, v160
	v_min_f32_e32 v161, 0, v161
	v_min_f32_e32 v162, 0, v162
	v_min_f32_e32 v163, 0, v163
	v_mul_f32_e32 v160, 0x3fb8aa3b, v160
	v_mul_f32_e32 v161, 0x3fb8aa3b, v161
	v_mul_f32_e32 v162, 0x3fb8aa3b, v162
	v_mul_f32_e32 v163, 0x3fb8aa3b, v163
	v_exp_f32_e32 v160, v160
	v_exp_f32_e32 v161, v161
	v_exp_f32_e32 v162, v162
	v_exp_f32_e32 v163, v163
	s_nop 0
	v_mul_f32_e32 v160, v28, v160
	v_mul_f32_e32 v161, v29, v161
	v_mul_f32_e32 v162, v30, v162
	v_mul_f32_e32 v163, v31, v163
	v_mul_f32_e32 v160, v160, v156
	v_mul_f32_e32 v161, v161, v157
	v_mul_f32_e32 v162, v162, v158
	v_mul_f32_e32 v163, v163, v159
	v_cndmask_b32_e64 v160, 0, v160, s[52:53]
	v_cndmask_b32_e64 v161, 0, v161, s[54:55]
	v_cndmask_b32_e64 v162, 0, v162, s[56:57]
	v_cndmask_b32_e64 v163, 0, v163, s[58:59]
	v_cvt_pk_bf16_f32 v164, v160, v161
	v_cvt_pk_bf16_f32 v165, v162, v163
	ds_write_b64 v189, v[164:165] offset:224
	s_branch .Lm3_h2_msdone

; DI float bf2f(unsigned short b) { return __uint_as_float((unsigned)b << 16); }
; DI unsigned short f2bf(float f) { return (unsigned short)(pk2(f, 0.f) & 0xffffu); }
; DI float silu_f(float x) { return x * fast_sigmoid(x); }
; DI float sum16(float v) { v += __shfl_xor(v, 1); v += __shfl_xor(v, 2); v += __shfl_xor(v, 4); v += __shfl_xor(v, 8); return v; }
; __global__ void __launch_bounds__(512, 2) fwd_megakernel(Args args) {
;     ...
;                         for (int j = 0; j < 4; ++j) {
;                             const int l = 16 * wave + q4 * 4 + j; const size_t row = grow0 + l; const float ea = __expf(acl[j]); float ss = 0.f;
; #pragma unroll
;                             for (int pt = 0; pt < 4; ++pt) {
;                                 const int p = 16 * pt + r16;
;                                 const float y = yd[pt][j] + ea * yo[pt][j] + Dh * bf2f(xh[p * 136 + l]);
;                                 const float o = y * silu_f(bf2f(zr[j][pt])); ss += o * o; Yg[row * DM + h * 64 + p] = f2bf(o);
;                             }
;                             ss = sum16(ss);
;                             if (r16 == 0) mss_g[((size_t)g2 * MTOK + row) * 4 + hh] = ss;
.Lm3_h2_yddone:
	s_nop 7
	s_nop 3
	v_lshlrev_b32_e32 v160, 16, v128
	v_and_b32_e32 v161, 0xffff0000, v128
	v_lshlrev_b32_e32 v162, 16, v129
	v_and_b32_e32 v163, 0xffff0000, v129
	v_lshlrev_b32_e32 v136, 16, v136
	v_lshlrev_b32_e32 v137, 16, v137
	v_lshlrev_b32_e32 v138, 16, v138
	v_lshlrev_b32_e32 v139, 16, v139
	v_fmac_f32_e32 v112, s38, v136
	v_fmac_f32_e32 v113, s38, v137
	v_fmac_f32_e32 v114, s38, v138
	v_fmac_f32_e32 v115, s38, v139
	v_mul_f32_e32 v164, 0xbfb8aa3b, v160
	v_mul_f32_e32 v165, 0xbfb8aa3b, v161
	v_mul_f32_e32 v166, 0xbfb8aa3b, v162
	v_mul_f32_e32 v167, 0xbfb8aa3b, v163
	v_exp_f32_e32 v164, v164
	v_exp_f32_e32 v165, v165
	v_exp_f32_e32 v166, v166
	v_exp_f32_e32 v167, v167
	s_nop 0
	v_add_f32_e32 v164, 1.0, v164
	v_add_f32_e32 v165, 1.0, v165
	v_add_f32_e32 v166, 1.0, v166
	v_add_f32_e32 v167, 1.0, v167
	v_rcp_f32_e32 v164, v164
	v_rcp_f32_e32 v165, v165
	v_rcp_f32_e32 v166, v166
	v_rcp_f32_e32 v167, v167
	s_nop 0
	v_mul_f32_e32 v164, v164, v160
	v_mul_f32_e32 v165, v165, v161
	v_mul_f32_e32 v166, v166, v162
	v_mul_f32_e32 v167, v167, v163
	v_mul_f32_e32 v164, v112, v164
	v_mul_f32_e32 v165, v113, v165
	v_mul_f32_e32 v166, v114, v166
	v_mul_f32_e32 v167, v115, v167
	v_mul_f32_e32 v208, v164, v164
	v_fmac_f32_e32 v208, v165, v165
	v_fmac_f32_e32 v208, v166, v166
	v_fmac_f32_e32 v208, v167, v167
	v_cvt_pk_bf16_f32 v168, v164, v165
	v_cvt_pk_bf16_f32 v169, v166, v167
	global_store_dwordx2 v185, v[168:169], s[12:13] offset:0
	v_lshlrev_b32_e32 v160, 16, v130
	v_and_b32_e32 v161, 0xffff0000, v130
	v_lshlrev_b32_e32 v162, 16, v131
	v_and_b32_e32 v163, 0xffff0000, v131
	v_lshlrev_b32_e32 v140, 16, v140
	v_lshlrev_b32_e32 v141, 16, v141
	v_lshlrev_b32_e32 v142, 16, v142
	v_lshlrev_b32_e32 v143, 16, v143
	v_fmac_f32_e32 v116, s38, v140
	v_fmac_f32_e32 v117, s38, v141
	v_fmac_f32_e32 v118, s38, v142
	v_fmac_f32_e32 v119, s38, v143
	v_mul_f32_e32 v164, 0xbfb8aa3b, v160
	v_mul_f32_e32 v165, 0xbfb8aa3b, v161
	v_mul_f32_e32 v166, 0xbfb8aa3b, v162
	v_mul_f32_e32 v167, 0xbfb8aa3b, v163
	v_exp_f32_e32 v164, v164
	v_exp_f32_e32 v165, v165
	v_exp_f32_e32 v166, v166
	v_exp_f32_e32 v167, v167
	s_nop 0
	v_add_f32_e32 v164, 1.0, v164
	v_add_f32_e32 v165, 1.0, v165
	v_add_f32_e32 v166, 1.0, v166
	v_add_f32_e32 v167, 1.0, v167
	v_rcp_f32_e32 v164, v164
	v_rcp_f32_e32 v165, v165
	v_rcp_f32_e32 v166, v166
	v_rcp_f32_e32 v167, v167
	s_nop 0
	v_mul_f32_e32 v164, v164, v160
	v_mul_f32_e32 v165, v165, v161
	v_mul_f32_e32 v166, v166, v162
	v_mul_f32_e32 v167, v167, v163
	v_mul_f32_e32 v164, v116, v164
	v_mul_f32_e32 v165, v117, v165
	v_mul_f32_e32 v166, v118, v166
	v_mul_f32_e32 v167, v119, v167
	v_fmac_f32_e32 v208, v164, v164
	v_fmac_f32_e32 v208, v165, v165
	v_fmac_f32_e32 v208, v166, v166
	v_fmac_f32_e32 v208, v167, v167
	v_cvt_pk_bf16_f32 v168, v164, v165
	v_cvt_pk_bf16_f32 v169, v166, v167
	global_store_dwordx2 v185, v[168:169], s[12:13] offset:32
	v_lshlrev_b32_e32 v160, 16, v132
	v_and_b32_e32 v161, 0xffff0000, v132
	v_lshlrev_b32_e32 v162, 16, v133
	v_and_b32_e32 v163, 0xffff0000, v133
	v_lshlrev_b32_e32 v144, 16, v144
	v_lshlrev_b32_e32 v145, 16, v145
	v_lshlrev_b32_e32 v146, 16, v146
	v_lshlrev_b32_e32 v147, 16, v147
	v_fmac_f32_e32 v120, s38, v144
	v_fmac_f32_e32 v121, s38, v145
	v_fmac_f32_e32 v122, s38, v146
	v_fmac_f32_e32 v123, s38, v147
	v_mul_f32_e32 v164, 0xbfb8aa3b, v160
	v_mul_f32_e32 v165, 0xbfb8aa3b, v161
	v_mul_f32_e32 v166, 0xbfb8aa3b, v162
	v_mul_f32_e32 v167, 0xbfb8aa3b, v163
	v_exp_f32_e32 v164, v164
	v_exp_f32_e32 v165, v165
	v_exp_f32_e32 v166, v166
	v_exp_f32_e32 v167, v167
	s_nop 0
	v_add_f32_e32 v164, 1.0, v164
	v_add_f32_e32 v165, 1.0, v165
	v_add_f32_e32 v166, 1.0, v166
	v_add_f32_e32 v167, 1.0, v167
	v_rcp_f32_e32 v164, v164
	v_rcp_f32_e32 v165, v165
	v_rcp_f32_e32 v166, v166
	v_rcp_f32_e32 v167, v167
	s_nop 0
	v_mul_f32_e32 v164, v164, v160
	v_mul_f32_e32 v165, v165, v161
	v_mul_f32_e32 v166, v166, v162
	v_mul_f32_e32 v167, v167, v163
	v_mul_f32_e32 v164, v120, v164
	v_mul_f32_e32 v165, v121, v165
	v_mul_f32_e32 v166, v122, v166
	v_mul_f32_e32 v167, v123, v167
	v_fmac_f32_e32 v208, v164, v164
	v_fmac_f32_e32 v208, v165, v165
	v_fmac_f32_e32 v208, v166, v166
	v_fmac_f32_e32 v208, v167, v167
	v_cvt_pk_bf16_f32 v168, v164, v165
	v_cvt_pk_bf16_f32 v169, v166, v167
	global_store_dwordx2 v185, v[168:169], s[12:13] offset:64
	v_lshlrev_b32_e32 v160, 16, v134
	v_and_b32_e32 v161, 0xffff0000, v134
	v_lshlrev_b32_e32 v162, 16, v135
	v_and_b32_e32 v163, 0xffff0000, v135
	v_lshlrev_b32_e32 v148, 16, v148
	v_lshlrev_b32_e32 v149, 16, v149
	v_lshlrev_b32_e32 v150, 16, v150
	v_lshlrev_b32_e32 v151, 16, v151
	v_fmac_f32_e32 v124, s38, v148
	v_fmac_f32_e32 v125, s38, v149
	v_fmac_f32_e32 v126, s38, v150
	v_fmac_f32_e32 v127, s38, v151
	v_mul_f32_e32 v164, 0xbfb8aa3b, v160
	v_mul_f32_e32 v165, 0xbfb8aa3b, v161
	v_mul_f32_e32 v166, 0xbfb8aa3b, v162
	v_mul_f32_e32 v167, 0xbfb8aa3b, v163
	v_exp_f32_e32 v164, v164
	v_exp_f32_e32 v165, v165
	v_exp_f32_e32 v166, v166
	v_exp_f32_e32 v167, v167
	s_nop 0
	v_add_f32_e32 v164, 1.0, v164
	v_add_f32_e32 v165, 1.0, v165
	v_add_f32_e32 v166, 1.0, v166
	v_add_f32_e32 v167, 1.0, v167
	v_rcp_f32_e32 v164, v164
	v_rcp_f32_e32 v165, v165
	v_rcp_f32_e32 v166, v166
	v_rcp_f32_e32 v167, v167
	s_nop 0
	v_mul_f32_e32 v164, v164, v160
	v_mul_f32_e32 v165, v165, v161
	v_mul_f32_e32 v166, v166, v162
	v_mul_f32_e32 v167, v167, v163
	v_mul_f32_e32 v164, v124, v164
	v_mul_f32_e32 v165, v125, v165
	v_mul_f32_e32 v166, v126, v166
	v_mul_f32_e32 v167, v127, v167
	v_fmac_f32_e32 v208, v164, v164
	v_fmac_f32_e32 v208, v165, v165
	v_fmac_f32_e32 v208, v166, v166
	v_fmac_f32_e32 v208, v167, v167
	v_cvt_pk_bf16_f32 v168, v164, v165
	v_cvt_pk_bf16_f32 v169, v166, v167
	global_store_dwordx2 v185, v[168:169], s[12:13] offset:96
	ds_bpermute_b32 v213, v211, v208
	s_waitcnt lgkmcnt(0)
; #define LAS __attribute__((address_space(3)))
; DI unsigned short f2bf(float f) { return (unsigned short)(pk2(f, 0.f) & 0xffffu); }
; DI float sum16(float v) { v += __shfl_xor(v, 1); v += __shfl_xor(v, 2); v += __shfl_xor(v, 4); v += __shfl_xor(v, 8); return v; }
; __global__ void __launch_bounds__(512, 2) fwd_megakernel(Args args) {
;     ...
;                         const LAS float* hdt = s_dt + hh * 128; const LAS float* hacs = s_acs + hh * 128;
;                         float acl[4];
; #pragma unroll
;                         for (int j = 0; j < 4; ++j) acl[j] = hacs[16 * wave + q4 * 4 + j];
; #pragma unroll
;                         for (int st = 0; st < 8; ++st) {
;                             if (st <= (wave | 1)) {
;                                 const int sI = 16 * st + r16; const float acss = hacs[sI], dts = hdt[sI];
; #pragma unroll
;                                 for (int j = 0; j < 4; ++j) { const int l = 16 * wave + q4 * 4 + j; const float mv = (sI <= l) ? cbr[st][j] * __expf(fminf(acl[j] - acss, 0.f)) * dts : 0.f; Ms[l * 136 + sI] = f2bf(mv); }
;                             }
;     ...
;                             ss = sum16(ss);
;                             if (r16 == 0) mss_g[((size_t)g2 * MTOK + row) * 4 + hh] = ss;
	v_add_f32_e32 v208, v208, v213
	ds_bpermute_b32 v213, v212, v208
	s_waitcnt lgkmcnt(0)
	v_add_f32_e32 v208, v208, v213
	s_mov_b64 exec, s[42:43]
	global_store_dword v186, v208, s[22:23]
	s_mov_b64 exec, -1
	s_add_u32 s12, s12, 0x80
	s_addc_u32 s13, s13, 0
	s_add_u32 s22, s22, 4
	s_addc_u32 s23, s23, 0
	v_add_u32_e32 v187, 0x200, v187
	v_add_u32_e32 v188, 0x200, v188
	v_add_u32_e32 v190, 0x4400, v190
	v_add_u32_e32 v191, 0x4400, v191
	ds_read_b32 v206, v187 offset:2048
	ds_read_b128 v[152:155], v188 offset:2048
	ds_read_b128 v[156:159], v188 offset:0
	s_cmp_eq_u32 s2, 0
	s_cselect_b64 s[52:53], s[44:45], -1
	s_cselect_b64 s[54:55], s[46:47], -1
	s_cselect_b64 s[56:57], s[48:49], -1
	s_cselect_b64 s[58:59], s[50:51], -1
	s_waitcnt lgkmcnt(0)
	v_sub_f32_e32 v160, v206, v152
	v_sub_f32_e32 v161, v206, v153
	v_sub_f32_e32 v162, v206, v154
	v_sub_f32_e32 v163, v206, v155
	v_min_f32_e32 v160, 0, v160
	v_min_f32_e32 v161, 0, v161
	v_min_f32_e32 v162, 0, v162
	v_min_f32_e32 v163, 0, v163
	v_mul_f32_e32 v160, 0x3fb8aa3b, v160
	v_mul_f32_e32 v161, 0x3fb8aa3b, v161
	v_mul_f32_e32 v162, 0x3fb8aa3b, v162
	v_mul_f32_e32 v163, 0x3fb8aa3b, v163
	v_exp_f32_e32 v160, v160
	v_exp_f32_e32 v161, v161
	v_exp_f32_e32 v162, v162
	v_exp_f32_e32 v163, v163
	s_nop 0
	v_mul_f32_e32 v160, v0, v160
	v_mul_f32_e32 v161, v1, v161
	v_mul_f32_e32 v162, v2, v162
	v_mul_f32_e32 v163, v3, v163
	v_mul_f32_e32 v160, v160, v156
	v_mul_f32_e32 v161, v161, v157
	v_mul_f32_e32 v162, v162, v158
	v_mul_f32_e32 v163, v163, v159
	v_cndmask_b32_e64 v160, 0, v160, s[52:53]
	v_cndmask_b32_e64 v161, 0, v161, s[54:55]
	v_cndmask_b32_e64 v162, 0, v162, s[56:57]
	v_cndmask_b32_e64 v163, 0, v163, s[58:59]
	v_cvt_pk_bf16_f32 v164, v160, v161
	v_cvt_pk_bf16_f32 v165, v162, v163
	ds_write_b64 v189, v[164:165] offset:0
	s_cmp_lt_u32 s2, 1
	s_cbranch_scc1 .Lm3_h3_skip1
	ds_read_b128 v[152:155], v188 offset:2112
	ds_read_b128 v[156:159], v188 offset:64
	s_cmp_eq_u32 s2, 1
	s_cselect_b64 s[52:53], s[44:45], -1
	s_cselect_b64 s[54:55], s[46:47], -1
	s_cselect_b64 s[56:57], s[48:49], -1
	s_cselect_b64 s[58:59], s[50:51], -1
	s_waitcnt lgkmcnt(0)
	v_sub_f32_e32 v160, v206, v152
	v_sub_f32_e32 v161, v206, v153
	v_sub_f32_e32 v162, v206, v154
	v_sub_f32_e32 v163, v206, v155
	v_min_f32_e32 v160, 0, v160
	v_min_f32_e32 v161, 0, v161
	v_min_f32_e32 v162, 0, v162
	v_min_f32_e32 v163, 0, v163
	v_mul_f32_e32 v160, 0x3fb8aa3b, v160
	v_mul_f32_e32 v161, 0x3fb8aa3b, v161
	v_mul_f32_e32 v162, 0x3fb8aa3b, v162
	v_mul_f32_e32 v163, 0x3fb8aa3b, v163
	v_exp_f32_e32 v160, v160
	v_exp_f32_e32 v161, v161
	v_exp_f32_e32 v162, v162
	v_exp_f32_e32 v163, v163
	s_nop 0
	v_mul_f32_e32 v160, v4, v160
	v_mul_f32_e32 v161, v5, v161
	v_mul_f32_e32 v162, v6, v162
	v_mul_f32_e32 v163, v7, v163
	v_mul_f32_e32 v160, v160, v156
	v_mul_f32_e32 v161, v161, v157
	v_mul_f32_e32 v162, v162, v158
	v_mul_f32_e32 v163, v163, v159
	v_cndmask_b32_e64 v160, 0, v160, s[52:53]
	v_cndmask_b32_e64 v161, 0, v161, s[54:55]
	v_cndmask_b32_e64 v162, 0, v162, s[56:57]
	v_cndmask_b32_e64 v163, 0, v163, s[58:59]
	v_cvt_pk_bf16_f32 v164, v160, v161
	v_cvt_pk_bf16_f32 v165, v162, v163
	ds_write_b64 v189, v[164:165] offset:32
	s_cmp_lt_u32 s2, 2
	s_cbranch_scc1 .Lm3_h3_skip2
	ds_read_b128 v[152:155], v188 offset:2176
	ds_read_b128 v[156:159], v188 offset:128
	s_cmp_eq_u32 s2, 2
	s_cselect_b64 s[52:53], s[44:45], -1
	s_cselect_b64 s[54:55], s[46:47], -1
	s_cselect_b64 s[56:57], s[48:49], -1
	s_cselect_b64 s[58:59], s[50:51], -1
	s_waitcnt lgkmcnt(0)
	v_sub_f32_e32 v160, v206, v152
	v_sub_f32_e32 v161, v206, v153
	v_sub_f32_e32 v162, v206, v154
	v_sub_f32_e32 v163, v206, v155
	v_min_f32_e32 v160, 0, v160
	v_min_f32_e32 v161, 0, v161
	v_min_f32_e32 v162, 0, v162
	v_min_f32_e32 v163, 0, v163
	v_mul_f32_e32 v160, 0x3fb8aa3b, v160
	v_mul_f32_e32 v161, 0x3fb8aa3b, v161
	v_mul_f32_e32 v162, 0x3fb8aa3b, v162
	v_mul_f32_e32 v163, 0x3fb8aa3b, v163
	v_exp_f32_e32 v160, v160
	v_exp_f32_e32 v161, v161
	v_exp_f32_e32 v162, v162
	v_exp_f32_e32 v163, v163
	s_nop 0
	v_mul_f32_e32 v160, v8, v160
	v_mul_f32_e32 v161, v9, v161
	v_mul_f32_e32 v162, v10, v162
	v_mul_f32_e32 v163, v11, v163
	v_mul_f32_e32 v160, v160, v156
	v_mul_f32_e32 v161, v161, v157
	v_mul_f32_e32 v162, v162, v158
	v_mul_f32_e32 v163, v163, v159
	v_cndmask_b32_e64 v160, 0, v160, s[52:53]
	v_cndmask_b32_e64 v161, 0, v161, s[54:55]
	v_cndmask_b32_e64 v162, 0, v162, s[56:57]
	v_cndmask_b32_e64 v163, 0, v163, s[58:59]
	v_cvt_pk_bf16_f32 v164, v160, v161
	v_cvt_pk_bf16_f32 v165, v162, v163
	ds_write_b64 v189, v[164:165] offset:64
	s_cmp_lt_u32 s2, 3
	s_cbranch_scc1 .Lm3_h3_skip3
	ds_read_b128 v[152:155], v188 offset:2240
	ds_read_b128 v[156:159], v188 offset:192
	s_cmp_eq_u32 s2, 3
	s_cselect_b64 s[52:53], s[44:45], -1
	s_cselect_b64 s[54:55], s[46:47], -1
	s_cselect_b64 s[56:57], s[48:49], -1
	s_cselect_b64 s[58:59], s[50:51], -1
	s_waitcnt lgkmcnt(0)
	v_sub_f32_e32 v160, v206, v152
	v_sub_f32_e32 v161, v206, v153
	v_sub_f32_e32 v162, v206, v154
	v_sub_f32_e32 v163, v206, v155
	v_min_f32_e32 v160, 0, v160
	v_min_f32_e32 v161, 0, v161
	v_min_f32_e32 v162, 0, v162
	v_min_f32_e32 v163, 0, v163
	v_mul_f32_e32 v160, 0x3fb8aa3b, v160
	v_mul_f32_e32 v161, 0x3fb8aa3b, v161
	v_mul_f32_e32 v162, 0x3fb8aa3b, v162
	v_mul_f32_e32 v163, 0x3fb8aa3b, v163
	v_exp_f32_e32 v160, v160
	v_exp_f32_e32 v161, v161
	v_exp_f32_e32 v162, v162
	v_exp_f32_e32 v163, v163
	s_nop 0
	v_mul_f32_e32 v160, v12, v160
	v_mul_f32_e32 v161, v13, v161
	v_mul_f32_e32 v162, v14, v162
	v_mul_f32_e32 v163, v15, v163
	v_mul_f32_e32 v160, v160, v156
	v_mul_f32_e32 v161, v161, v157
	v_mul_f32_e32 v162, v162, v158
	v_mul_f32_e32 v163, v163, v159
	v_cndmask_b32_e64 v160, 0, v160, s[52:53]
	v_cndmask_b32_e64 v161, 0, v161, s[54:55]
	v_cndmask_b32_e64 v162, 0, v162, s[56:57]
	v_cndmask_b32_e64 v163, 0, v163, s[58:59]
	v_cvt_pk_bf16_f32 v164, v160, v161
	v_cvt_pk_bf16_f32 v165, v162, v163
	ds_write_b64 v189, v[164:165] offset:96
	s_cmp_lt_u32 s2, 4
	s_cbranch_scc1 .Lm3_h3_skip4
; DI unsigned short f2bf(float f) { return (unsigned short)(pk2(f, 0.f) & 0xffffu); }
; __global__ void __launch_bounds__(512, 2) fwd_megakernel(Args args) {
;     ...
;                         for (int st = 0; st < 8; ++st) {
;                             if (st <= (wave | 1)) {
;                                 const int sI = 16 * st + r16; const float acss = hacs[sI], dts = hdt[sI];
; #pragma unroll
;                                 for (int j = 0; j < 4; ++j) { const int l = 16 * wave + q4 * 4 + j; const float mv = (sI <= l) ? cbr[st][j] * __expf(fminf(acl[j] - acss, 0.f)) * dts : 0.f; Ms[l * 136 + sI] = f2bf(mv); }
;                             }
	ds_read_b128 v[152:155], v188 offset:2304
	ds_read_b128 v[156:159], v188 offset:256
	s_cmp_eq_u32 s2, 4
	s_cselect_b64 s[52:53], s[44:45], -1
	s_cselect_b64 s[54:55], s[46:47], -1
	s_cselect_b64 s[56:57], s[48:49], -1
	s_cselect_b64 s[58:59], s[50:51], -1
	s_waitcnt lgkmcnt(0)
	v_sub_f32_e32 v160, v206, v152
	v_sub_f32_e32 v161, v206, v153
	v_sub_f32_e32 v162, v206, v154
	v_sub_f32_e32 v163, v206, v155
	v_min_f32_e32 v160, 0, v160
	v_min_f32_e32 v161, 0, v161
	v_min_f32_e32 v162, 0, v162
	v_min_f32_e32 v163, 0, v163
	v_mul_f32_e32 v160, 0x3fb8aa3b, v160
	v_mul_f32_e32 v161, 0x3fb8aa3b, v161
	v_mul_f32_e32 v162, 0x3fb8aa3b, v162
	v_mul_f32_e32 v163, 0x3fb8aa3b, v163
	v_exp_f32_e32 v160, v160
	v_exp_f32_e32 v161, v161
	v_exp_f32_e32 v162, v162
	v_exp_f32_e32 v163, v163
	s_nop 0
	v_mul_f32_e32 v160, v16, v160
	v_mul_f32_e32 v161, v17, v161
	v_mul_f32_e32 v162, v18, v162
	v_mul_f32_e32 v163, v19, v163
	v_mul_f32_e32 v160, v160, v156
	v_mul_f32_e32 v161, v161, v157
	v_mul_f32_e32 v162, v162, v158
	v_mul_f32_e32 v163, v163, v159
	v_cndmask_b32_e64 v160, 0, v160, s[52:53]
	v_cndmask_b32_e64 v161, 0, v161, s[54:55]
	v_cndmask_b32_e64 v162, 0, v162, s[56:57]
	v_cndmask_b32_e64 v163, 0, v163, s[58:59]
	v_cvt_pk_bf16_f32 v164, v160, v161
	v_cvt_pk_bf16_f32 v165, v162, v163
	ds_write_b64 v189, v[164:165] offset:128
	s_cmp_lt_u32 s2, 5
	s_cbranch_scc1 .Lm3_h3_skip5
	ds_read_b128 v[152:155], v188 offset:2368
	ds_read_b128 v[156:159], v188 offset:320
	s_cmp_eq_u32 s2, 5
	s_cselect_b64 s[52:53], s[44:45], -1
	s_cselect_b64 s[54:55], s[46:47], -1
	s_cselect_b64 s[56:57], s[48:49], -1
	s_cselect_b64 s[58:59], s[50:51], -1
	s_waitcnt lgkmcnt(0)
	v_sub_f32_e32 v160, v206, v152
	v_sub_f32_e32 v161, v206, v153
	v_sub_f32_e32 v162, v206, v154
	v_sub_f32_e32 v163, v206, v155
	v_min_f32_e32 v160, 0, v160
	v_min_f32_e32 v161, 0, v161
	v_min_f32_e32 v162, 0, v162
	v_min_f32_e32 v163, 0, v163
	v_mul_f32_e32 v160, 0x3fb8aa3b, v160
	v_mul_f32_e32 v161, 0x3fb8aa3b, v161
	v_mul_f32_e32 v162, 0x3fb8aa3b, v162
	v_mul_f32_e32 v163, 0x3fb8aa3b, v163
	v_exp_f32_e32 v160, v160
	v_exp_f32_e32 v161, v161
	v_exp_f32_e32 v162, v162
	v_exp_f32_e32 v163, v163
	s_nop 0
	v_mul_f32_e32 v160, v20, v160
	v_mul_f32_e32 v161, v21, v161
	v_mul_f32_e32 v162, v22, v162
	v_mul_f32_e32 v163, v23, v163
	v_mul_f32_e32 v160, v160, v156
	v_mul_f32_e32 v161, v161, v157
	v_mul_f32_e32 v162, v162, v158
	v_mul_f32_e32 v163, v163, v159
	v_cndmask_b32_e64 v160, 0, v160, s[52:53]
	v_cndmask_b32_e64 v161, 0, v161, s[54:55]
	v_cndmask_b32_e64 v162, 0, v162, s[56:57]
	v_cndmask_b32_e64 v163, 0, v163, s[58:59]
	v_cvt_pk_bf16_f32 v164, v160, v161
	v_cvt_pk_bf16_f32 v165, v162, v163
	ds_write_b64 v189, v[164:165] offset:160
	s_cmp_lt_u32 s2, 6
	s_cbranch_scc1 .Lm3_h3_skip6
	ds_read_b128 v[152:155], v188 offset:2432
	ds_read_b128 v[156:159], v188 offset:384
	s_cmp_eq_u32 s2, 6
	s_cselect_b64 s[52:53], s[44:45], -1
	s_cselect_b64 s[54:55], s[46:47], -1
	s_cselect_b64 s[56:57], s[48:49], -1
	s_cselect_b64 s[58:59], s[50:51], -1
	s_waitcnt lgkmcnt(0)
	v_sub_f32_e32 v160, v206, v152
	v_sub_f32_e32 v161, v206, v153
	v_sub_f32_e32 v162, v206, v154
	v_sub_f32_e32 v163, v206, v155
	v_min_f32_e32 v160, 0, v160
	v_min_f32_e32 v161, 0, v161
	v_min_f32_e32 v162, 0, v162
	v_min_f32_e32 v163, 0, v163
	v_mul_f32_e32 v160, 0x3fb8aa3b, v160
	v_mul_f32_e32 v161, 0x3fb8aa3b, v161
	v_mul_f32_e32 v162, 0x3fb8aa3b, v162
	v_mul_f32_e32 v163, 0x3fb8aa3b, v163
	v_exp_f32_e32 v160, v160
	v_exp_f32_e32 v161, v161
	v_exp_f32_e32 v162, v162
	v_exp_f32_e32 v163, v163
	s_nop 0
	v_mul_f32_e32 v160, v24, v160
	v_mul_f32_e32 v161, v25, v161
	v_mul_f32_e32 v162, v26, v162
	v_mul_f32_e32 v163, v27, v163
	v_mul_f32_e32 v160, v160, v156
	v_mul_f32_e32 v161, v161, v157
	v_mul_f32_e32 v162, v162, v158
	v_mul_f32_e32 v163, v163, v159
	v_cndmask_b32_e64 v160, 0, v160, s[52:53]
	v_cndmask_b32_e64 v161, 0, v161, s[54:55]
	v_cndmask_b32_e64 v162, 0, v162, s[56:57]
	v_cndmask_b32_e64 v163, 0, v163, s[58:59]
	v_cvt_pk_bf16_f32 v164, v160, v161
	v_cvt_pk_bf16_f32 v165, v162, v163
	ds_write_b64 v189, v[164:165] offset:192
	s_cmp_lt_u32 s2, 7
	s_cbranch_scc1 .Lm3_h3_skip7
	ds_read_b128 v[152:155], v188 offset:2496
	ds_read_b128 v[156:159], v188 offset:448
	s_cmp_eq_u32 s2, 7
	s_cselect_b64 s[52:53], s[44:45], -1
	s_cselect_b64 s[54:55], s[46:47], -1
	s_cselect_b64 s[56:57], s[48:49], -1
	s_cselect_b64 s[58:59], s[50:51], -1
	s_waitcnt lgkmcnt(0)
	v_sub_f32_e32 v160, v206, v152
	v_sub_f32_e32 v161, v206, v153
	v_sub_f32_e32 v162, v206, v154
	v_sub_f32_e32 v163, v206, v155
	v_min_f32_e32 v160, 0, v160
	v_min_f32_e32 v161, 0, v161
	v_min_f32_e32 v162, 0, v162
	v_min_f32_e32 v163, 0, v163
	v_mul_f32_e32 v160, 0x3fb8aa3b, v160
	v_mul_f32_e32 v161, 0x3fb8aa3b, v161
	v_mul_f32_e32 v162, 0x3fb8aa3b, v162
	v_mul_f32_e32 v163, 0x3fb8aa3b, v163
	v_exp_f32_e32 v160, v160
	v_exp_f32_e32 v161, v161
	v_exp_f32_e32 v162, v162
	v_exp_f32_e32 v163, v163
	s_nop 0
	v_mul_f32_e32 v160, v28, v160
	v_mul_f32_e32 v161, v29, v161
	v_mul_f32_e32 v162, v30, v162
	v_mul_f32_e32 v163, v31, v163
	v_mul_f32_e32 v160, v160, v156
	v_mul_f32_e32 v161, v161, v157
	v_mul_f32_e32 v162, v162, v158
	v_mul_f32_e32 v163, v163, v159
	v_cndmask_b32_e64 v160, 0, v160, s[52:53]
	v_cndmask_b32_e64 v161, 0, v161, s[54:55]
	v_cndmask_b32_e64 v162, 0, v162, s[56:57]
	v_cndmask_b32_e64 v163, 0, v163, s[58:59]
	v_cvt_pk_bf16_f32 v164, v160, v161
	v_cvt_pk_bf16_f32 v165, v162, v163
	ds_write_b64 v189, v[164:165] offset:224
	s_branch .Lm3_h3_msdone

; #define LAS __attribute__((address_space(3)))
; DI f32x4 mfma16(bf16x8 a, bf16x8 b, f32x4 c) { return __builtin_amdgcn_mfma_f32_16x16x32_bf16(a, b, c, 0, 0, 0); }
; __global__ void __launch_bounds__(512, 2) fwd_megakernel(Args args) {
;     ...
;                         f32x4 yo[4], yd[4];
; #pragma unroll
;                         for (int pt = 0; pt < 4; ++pt) { yo[pt] = (f32x4){0.f, 0.f, 0.f, 0.f}; yd[pt] = (f32x4){0.f, 0.f, 0.f, 0.f}; }
;                         const LAS bf16* xh = xT + hh * (64 * 136);
; #pragma unroll
;                         for (int ks = 0; ks < 4; ++ks) {
;                             if (2 * ks <= wave) {
;                                 const bf16x8 ma = lds_frag(Ms, lrow, 136, ks * 32 + q4 * 8);
; #pragma unroll
;                                 for (int pt = 0; pt < 4; ++pt) yd[pt] = mfma16(ma, lds_frag(xh, 16 * pt + r16, 136, ks * 32 + q4 * 8), yd[pt]);
;                             }
;                         }
; #pragma unroll
;                         for (int ks = 0; ks < 4; ++ks)
; #pragma unroll
;                             for (int pt = 0; pt < 4; ++pt) yo[pt] = mfma16(ca[ks], pvf[ks][pt], yo[pt]);
.Lm3_h3_msdone:
	v_mul_f32_e32 v207, 0x3fb8aa3b, v206
	v_exp_f32_e32 v207, v207
	ds_read_u16 v136, v191 offset:0
	ds_read_u16 v137, v191 offset:272
	ds_read_u16 v138, v191 offset:544
	ds_read_u16 v139, v191 offset:816
	ds_read_u16 v140, v191 offset:4352
	ds_read_u16 v141, v191 offset:4624
	ds_read_u16 v142, v191 offset:4896
	ds_read_u16 v143, v191 offset:5168
	ds_read_u16 v144, v191 offset:8704
	ds_read_u16 v145, v191 offset:8976
	ds_read_u16 v146, v191 offset:9248
	ds_read_u16 v147, v191 offset:9520
	ds_read_u16 v148, v191 offset:13056
	ds_read_u16 v149, v191 offset:13328
	ds_read_u16 v150, v191 offset:13600
	ds_read_u16 v151, v191 offset:13872
	s_waitcnt vmcnt(0)
	v_mfma_f32_16x16x32_bf16 v[112:115], v[48:51], v[32:35], 0
	v_mfma_f32_16x16x32_bf16 v[116:119], v[52:55], v[32:35], 0
	v_mfma_f32_16x16x32_bf16 v[120:123], v[56:59], v[32:35], 0
	v_mfma_f32_16x16x32_bf16 v[124:127], v[60:63], v[32:35], 0
	v_mfma_f32_16x16x32_bf16 v[112:115], v[64:67], v[36:39], v[112:115]
	v_mfma_f32_16x16x32_bf16 v[116:119], v[68:71], v[36:39], v[116:119]
	v_mfma_f32_16x16x32_bf16 v[120:123], v[72:75], v[36:39], v[120:123]
	v_mfma_f32_16x16x32_bf16 v[124:127], v[76:79], v[36:39], v[124:127]
	v_mfma_f32_16x16x32_bf16 v[112:115], v[80:83], v[40:43], v[112:115]
	v_mfma_f32_16x16x32_bf16 v[116:119], v[84:87], v[40:43], v[116:119]
	v_mfma_f32_16x16x32_bf16 v[120:123], v[88:91], v[40:43], v[120:123]
	v_mfma_f32_16x16x32_bf16 v[124:127], v[92:95], v[40:43], v[124:127]
	v_mfma_f32_16x16x32_bf16 v[112:115], v[96:99], v[44:47], v[112:115]
	v_mfma_f32_16x16x32_bf16 v[116:119], v[100:103], v[44:47], v[116:119]
	v_mfma_f32_16x16x32_bf16 v[120:123], v[104:107], v[44:47], v[120:123]
	v_mfma_f32_16x16x32_bf16 v[124:127], v[108:111], v[44:47], v[124:127]
	s_nop 7
	s_nop 3
	v_mul_f32_e32 v112, v207, v112
	v_mul_f32_e32 v113, v207, v113
	v_mul_f32_e32 v114, v207, v114
	v_mul_f32_e32 v115, v207, v115
	v_mul_f32_e32 v116, v207, v116
	v_mul_f32_e32 v117, v207, v117
	v_mul_f32_e32 v118, v207, v118
	v_mul_f32_e32 v119, v207, v119
	v_mul_f32_e32 v120, v207, v120
	v_mul_f32_e32 v121, v207, v121
	v_mul_f32_e32 v122, v207, v122
	v_mul_f32_e32 v123, v207, v123
	v_mul_f32_e32 v124, v207, v124
	v_mul_f32_e32 v125, v207, v125
	v_mul_f32_e32 v126, v207, v126
	v_mul_f32_e32 v127, v207, v127
	s_waitcnt lgkmcnt(0)
	ds_read_b128 v[160:163], v179 offset:34816
	ds_read_b128 v[164:167], v190 offset:0
	ds_read_b128 v[168:171], v190 offset:4352
	ds_read_b128 v[172:175], v190 offset:8704
	ds_read_b128 v[152:155], v190 offset:13056
	s_waitcnt lgkmcnt(0)
	v_mfma_f32_16x16x32_bf16 v[112:115], v[164:167], v[160:163], v[112:115]
	v_mfma_f32_16x16x32_bf16 v[116:119], v[168:171], v[160:163], v[116:119]
	v_mfma_f32_16x16x32_bf16 v[120:123], v[172:175], v[160:163], v[120:123]
	v_mfma_f32_16x16x32_bf16 v[124:127], v[152:155], v[160:163], v[124:127]
	s_cmp_lt_u32 s2, 2
	s_cbranch_scc1 .Lm3_h3_yddone
	ds_read_b128 v[160:163], v179 offset:34880
	ds_read_b128 v[164:167], v190 offset:64
	ds_read_b128 v[168:171], v190 offset:4416
	ds_read_b128 v[172:175], v190 offset:8768
	ds_read_b128 v[152:155], v190 offset:13120
	s_waitcnt lgkmcnt(0)
	v_mfma_f32_16x16x32_bf16 v[112:115], v[164:167], v[160:163], v[112:115]
	v_mfma_f32_16x16x32_bf16 v[116:119], v[168:171], v[160:163], v[116:119]
	v_mfma_f32_16x16x32_bf16 v[120:123], v[172:175], v[160:163], v[120:123]
	v_mfma_f32_16x16x32_bf16 v[124:127], v[152:155], v[160:163], v[124:127]
	s_cmp_lt_u32 s2, 4
	s_cbranch_scc1 .Lm3_h3_yddone
	ds_read_b128 v[160:163], v179 offset:34944
	ds_read_b128 v[164:167], v190 offset:128
	ds_read_b128 v[168:171], v190 offset:4480
	ds_read_b128 v[172:175], v190 offset:8832
	ds_read_b128 v[152:155], v190 offset:13184
	s_waitcnt lgkmcnt(0)
	v_mfma_f32_16x16x32_bf16 v[112:115], v[164:167], v[160:163], v[112:115]
	v_mfma_f32_16x16x32_bf16 v[116:119], v[168:171], v[160:163], v[116:119]
	v_mfma_f32_16x16x32_bf16 v[120:123], v[172:175], v[160:163], v[120:123]
	v_mfma_f32_16x16x32_bf16 v[124:127], v[152:155], v[160:163], v[124:127]
	s_cmp_lt_u32 s2, 6
	s_cbranch_scc1 .Lm3_h3_yddone
	ds_read_b128 v[160:163], v179 offset:35008
	ds_read_b128 v[164:167], v190 offset:192
	ds_read_b128 v[168:171], v190 offset:4544
	ds_read_b128 v[172:175], v190 offset:8896
	ds_read_b128 v[152:155], v190 offset:13248
	s_waitcnt lgkmcnt(0)
	v_mfma_f32_16x16x32_bf16 v[112:115], v[164:167], v[160:163], v[112:115]
	v_mfma_f32_16x16x32_bf16 v[116:119], v[168:171], v[160:163], v[116:119]
	v_mfma_f32_16x16x32_bf16 v[120:123], v[172:175], v[160:163], v[120:123]
	v_mfma_f32_16x16x32_bf16 v[124:127], v[152:155], v[160:163], v[124:127]
; DI float bf2f(unsigned short b) { return __uint_as_float((unsigned)b << 16); }
; DI unsigned short f2bf(float f) { return (unsigned short)(pk2(f, 0.f) & 0xffffu); }
; DI float silu_f(float x) { return x * fast_sigmoid(x); }
; DI float sum16(float v) { v += __shfl_xor(v, 1); v += __shfl_xor(v, 2); v += __shfl_xor(v, 4); v += __shfl_xor(v, 8); return v; }
; __global__ void __launch_bounds__(512, 2) fwd_megakernel(Args args) {
;     ...
;                         for (int j = 0; j < 4; ++j) {
;                             const int l = 16 * wave + q4 * 4 + j; const size_t row = grow0 + l; const float ea = __expf(acl[j]); float ss = 0.f;
; #pragma unroll
;                             for (int pt = 0; pt < 4; ++pt) {
;                                 const int p = 16 * pt + r16;
;                                 const float y = yd[pt][j] + ea * yo[pt][j] + Dh * bf2f(xh[p * 136 + l]);
;                                 const float o = y * silu_f(bf2f(zr[j][pt])); ss += o * o; Yg[row * DM + h * 64 + p] = f2bf(o);
;                             }
;                             ss = sum16(ss);
;                             if (r16 == 0) mss_g[((size_t)g2 * MTOK + row) * 4 + hh] = ss;
.Lm3_h3_yddone:
	s_nop 7
	s_nop 3
	v_lshlrev_b32_e32 v160, 16, v196
	v_and_b32_e32 v161, 0xffff0000, v196
	v_lshlrev_b32_e32 v162, 16, v197
	v_and_b32_e32 v163, 0xffff0000, v197
	v_lshlrev_b32_e32 v136, 16, v136
	v_lshlrev_b32_e32 v137, 16, v137
	v_lshlrev_b32_e32 v138, 16, v138
	v_lshlrev_b32_e32 v139, 16, v139
	v_fmac_f32_e32 v112, s39, v136
	v_fmac_f32_e32 v113, s39, v137
	v_fmac_f32_e32 v114, s39, v138
	v_fmac_f32_e32 v115, s39, v139
	v_mul_f32_e32 v164, 0xbfb8aa3b, v160
	v_mul_f32_e32 v165, 0xbfb8aa3b, v161
	v_mul_f32_e32 v166, 0xbfb8aa3b, v162
	v_mul_f32_e32 v167, 0xbfb8aa3b, v163
	v_exp_f32_e32 v164, v164
	v_exp_f32_e32 v165, v165
	v_exp_f32_e32 v166, v166
	v_exp_f32_e32 v167, v167
	s_nop 0
	v_add_f32_e32 v164, 1.0, v164
	v_add_f32_e32 v165, 1.0, v165
	v_add_f32_e32 v166, 1.0, v166
	v_add_f32_e32 v167, 1.0, v167
	v_rcp_f32_e32 v164, v164
	v_rcp_f32_e32 v165, v165
	v_rcp_f32_e32 v166, v166
	v_rcp_f32_e32 v167, v167
	s_nop 0
	v_mul_f32_e32 v164, v164, v160
	v_mul_f32_e32 v165, v165, v161
	v_mul_f32_e32 v166, v166, v162
	v_mul_f32_e32 v167, v167, v163
	v_mul_f32_e32 v164, v112, v164
	v_mul_f32_e32 v165, v113, v165
	v_mul_f32_e32 v166, v114, v166
	v_mul_f32_e32 v167, v115, v167
	v_mul_f32_e32 v208, v164, v164
	v_fmac_f32_e32 v208, v165, v165
	v_fmac_f32_e32 v208, v166, v166
	v_fmac_f32_e32 v208, v167, v167
	v_cvt_pk_bf16_f32 v168, v164, v165
	v_cvt_pk_bf16_f32 v169, v166, v167
	global_store_dwordx2 v185, v[168:169], s[12:13] offset:0
	v_lshlrev_b32_e32 v160, 16, v198
	v_and_b32_e32 v161, 0xffff0000, v198
	v_lshlrev_b32_e32 v162, 16, v199
	v_and_b32_e32 v163, 0xffff0000, v199
	v_lshlrev_b32_e32 v140, 16, v140
	v_lshlrev_b32_e32 v141, 16, v141
	v_lshlrev_b32_e32 v142, 16, v142
	v_lshlrev_b32_e32 v143, 16, v143
	v_fmac_f32_e32 v116, s39, v140
	v_fmac_f32_e32 v117, s39, v141
	v_fmac_f32_e32 v118, s39, v142
	v_fmac_f32_e32 v119, s39, v143
	v_mul_f32_e32 v164, 0xbfb8aa3b, v160
	v_mul_f32_e32 v165, 0xbfb8aa3b, v161
	v_mul_f32_e32 v166, 0xbfb8aa3b, v162
	v_mul_f32_e32 v167, 0xbfb8aa3b, v163
	v_exp_f32_e32 v164, v164
	v_exp_f32_e32 v165, v165
	v_exp_f32_e32 v166, v166
	v_exp_f32_e32 v167, v167
	s_nop 0
	v_add_f32_e32 v164, 1.0, v164
	v_add_f32_e32 v165, 1.0, v165
	v_add_f32_e32 v166, 1.0, v166
	v_add_f32_e32 v167, 1.0, v167
	v_rcp_f32_e32 v164, v164
	v_rcp_f32_e32 v165, v165
	v_rcp_f32_e32 v166, v166
	v_rcp_f32_e32 v167, v167
	s_nop 0
	v_mul_f32_e32 v164, v164, v160
	v_mul_f32_e32 v165, v165, v161
	v_mul_f32_e32 v166, v166, v162
	v_mul_f32_e32 v167, v167, v163
	v_mul_f32_e32 v164, v116, v164
	v_mul_f32_e32 v165, v117, v165
	v_mul_f32_e32 v166, v118, v166
	v_mul_f32_e32 v167, v119, v167
	v_fmac_f32_e32 v208, v164, v164
	v_fmac_f32_e32 v208, v165, v165
	v_fmac_f32_e32 v208, v166, v166
	v_fmac_f32_e32 v208, v167, v167
	v_cvt_pk_bf16_f32 v168, v164, v165
	v_cvt_pk_bf16_f32 v169, v166, v167
	global_store_dwordx2 v185, v[168:169], s[12:13] offset:32
	v_lshlrev_b32_e32 v160, 16, v202
	v_and_b32_e32 v161, 0xffff0000, v202
	v_lshlrev_b32_e32 v162, 16, v203
	v_and_b32_e32 v163, 0xffff0000, v203
	v_lshlrev_b32_e32 v144, 16, v144
	v_lshlrev_b32_e32 v145, 16, v145
	v_lshlrev_b32_e32 v146, 16, v146
	v_lshlrev_b32_e32 v147, 16, v147
	v_fmac_f32_e32 v120, s39, v144
	v_fmac_f32_e32 v121, s39, v145
	v_fmac_f32_e32 v122, s39, v146
	v_fmac_f32_e32 v123, s39, v147
	v_mul_f32_e32 v164, 0xbfb8aa3b, v160
	v_mul_f32_e32 v165, 0xbfb8aa3b, v161
	v_mul_f32_e32 v166, 0xbfb8aa3b, v162
	v_mul_f32_e32 v167, 0xbfb8aa3b, v163
	v_exp_f32_e32 v164, v164
	v_exp_f32_e32 v165, v165
	v_exp_f32_e32 v166, v166
	v_exp_f32_e32 v167, v167
	s_nop 0
	v_add_f32_e32 v164, 1.0, v164
	v_add_f32_e32 v165, 1.0, v165
	v_add_f32_e32 v166, 1.0, v166
	v_add_f32_e32 v167, 1.0, v167
	v_rcp_f32_e32 v164, v164
	v_rcp_f32_e32 v165, v165
	v_rcp_f32_e32 v166, v166
	v_rcp_f32_e32 v167, v167
	s_nop 0
	v_mul_f32_e32 v164, v164, v160
	v_mul_f32_e32 v165, v165, v161
	v_mul_f32_e32 v166, v166, v162
	v_mul_f32_e32 v167, v167, v163
	v_mul_f32_e32 v164, v120, v164
	v_mul_f32_e32 v165, v121, v165
	v_mul_f32_e32 v166, v122, v166
	v_mul_f32_e32 v167, v123, v167
	v_fmac_f32_e32 v208, v164, v164
	v_fmac_f32_e32 v208, v165, v165
	v_fmac_f32_e32 v208, v166, v166
	v_fmac_f32_e32 v208, v167, v167
	v_cvt_pk_bf16_f32 v168, v164, v165
	v_cvt_pk_bf16_f32 v169, v166, v167
	global_store_dwordx2 v185, v[168:169], s[12:13] offset:64
	v_lshlrev_b32_e32 v160, 16, v204
	v_and_b32_e32 v161, 0xffff0000, v204
	v_lshlrev_b32_e32 v162, 16, v205
	v_and_b32_e32 v163, 0xffff0000, v205
	v_lshlrev_b32_e32 v148, 16, v148
	v_lshlrev_b32_e32 v149, 16, v149
	v_lshlrev_b32_e32 v150, 16, v150
	v_lshlrev_b32_e32 v151, 16, v151
	v_fmac_f32_e32 v124, s39, v148
	v_fmac_f32_e32 v125, s39, v149
	v_fmac_f32_e32 v126, s39, v150
	v_fmac_f32_e32 v127, s39, v151
	v_mul_f32_e32 v164, 0xbfb8aa3b, v160
	v_mul_f32_e32 v165, 0xbfb8aa3b, v161
	v_mul_f32_e32 v166, 0xbfb8aa3b, v162
	v_mul_f32_e32 v167, 0xbfb8aa3b, v163
	v_exp_f32_e32 v164, v164
	v_exp_f32_e32 v165, v165
	v_exp_f32_e32 v166, v166
	v_exp_f32_e32 v167, v167
	s_nop 0
	v_add_f32_e32 v164, 1.0, v164
	v_add_f32_e32 v165, 1.0, v165
	v_add_f32_e32 v166, 1.0, v166
	v_add_f32_e32 v167, 1.0, v167
	v_rcp_f32_e32 v164, v164
	v_rcp_f32_e32 v165, v165
	v_rcp_f32_e32 v166, v166
	v_rcp_f32_e32 v167, v167
	s_nop 0
	v_mul_f32_e32 v164, v164, v160
	v_mul_f32_e32 v165, v165, v161
	v_mul_f32_e32 v166, v166, v162
	v_mul_f32_e32 v167, v167, v163
	v_mul_f32_e32 v164, v124, v164
	v_mul_f32_e32 v165, v125, v165
	v_mul_f32_e32 v166, v126, v166
	v_mul_f32_e32 v167, v127, v167
	v_fmac_f32_e32 v208, v164, v164
	v_fmac_f32_e32 v208, v165, v165
	v_fmac_f32_e32 v208, v166, v166
	v_fmac_f32_e32 v208, v167, v167
	v_cvt_pk_bf16_f32 v168, v164, v165
	v_cvt_pk_bf16_f32 v169, v166, v167
	global_store_dwordx2 v185, v[168:169], s[12:13] offset:96
	ds_bpermute_b32 v213, v211, v208
	s_waitcnt lgkmcnt(0)
	v_add_f32_e32 v208, v208, v213
	ds_bpermute_b32 v213, v212, v208
	s_waitcnt lgkmcnt(0)
	v_add_f32_e32 v208, v208, v213
	s_mov_b64 exec, s[42:43]
	global_store_dword v186, v208, s[22:23]
	s_mov_b64 exec, -1
	s_branch .LBB0_928
